# residual-add epilogues of the output-projection and FFN-down phases: 32 tile loads issued up front with counted vmcnt, batched row-sum reductions
# speedup vs baseline: 1.0221x; 1.0221x over previous
.LBB0_1322:
	s_add_i32 s69, s42, 2
	s_add_u32 s40, s38, 0x100
	s_addc_u32 s41, s39, 0
	s_add_i32 s70, 0, 0x10000
	v_add_u32_e32 v146, s70, v170
	s_waitcnt lgkmcnt(0)
	ds_read_b128 v[128:131], v146
	ds_read_b128 v[138:141], v146 offset:1024
	ds_read_b128 v[142:145], v146 offset:2048
	ds_read_b128 v[146:149], v146 offset:3072
	s_cmp_eq_u32 s66, s42
	s_cselect_b32 s42, s65, s67
	s_cselect_b32 s45, s13, s41
	s_cselect_b32 s44, s23, s40
	s_cselect_b32 s43, s64, s68
	v_lshl_add_u64 v[166:167], s[38:39], 0, v[134:135]
	s_add_i32 m0, s51, 0xc000
	ds_read_b128 v[150:153], v171
	ds_read_b128 v[154:157], v171 offset:1024
	ds_read_b128 v[158:161], v171 offset:2048
	ds_read_b128 v[162:165], v171 offset:3072
	ds_read_b128 v[172:175], v171 offset:4096
	ds_read_b128 v[190:193], v171 offset:5120
	ds_read_b128 v[194:197], v171 offset:6144
	ds_read_b128 v[198:201], v171 offset:7168
	global_load_lds_dwordx4 v[166:167], off
	v_lshl_add_u64 v[166:167], s[38:39], 0, v[136:137]
	s_add_i32 m0, s51, 0xe000
	s_nop 0
	global_load_lds_dwordx4 v[166:167], off
	s_waitcnt lgkmcnt(8)
	s_barrier
	s_waitcnt lgkmcnt(0)
	s_setprio 1
	s_waitcnt lgkmcnt(0)
	v_mfma_f32_16x16x32_bf16 v[124:127], v[128:131], v[150:153], v[124:127]
	v_mfma_f32_16x16x32_bf16 v[120:123], v[142:145], v[150:153], v[120:123]
	v_mfma_f32_16x16x32_bf16 v[116:119], v[128:131], v[158:161], v[116:119]
	v_mfma_f32_16x16x32_bf16 v[112:115], v[142:145], v[158:161], v[112:115]
	v_mfma_f32_16x16x32_bf16 v[104:107], v[128:131], v[172:175], v[104:107]
	v_mfma_f32_16x16x32_bf16 v[96:99], v[142:145], v[172:175], v[96:99]
	v_mfma_f32_16x16x32_bf16 v[88:91], v[128:131], v[194:197], v[88:91]
	v_mfma_f32_16x16x32_bf16 v[80:83], v[142:145], v[194:197], v[80:83]
	v_mfma_f32_16x16x32_bf16 v[124:127], v[138:141], v[154:157], v[124:127]
	v_mfma_f32_16x16x32_bf16 v[120:123], v[146:149], v[154:157], v[120:123]
	v_mfma_f32_16x16x32_bf16 v[116:119], v[138:141], v[162:165], v[116:119]
	v_mfma_f32_16x16x32_bf16 v[112:115], v[146:149], v[162:165], v[112:115]
	v_mfma_f32_16x16x32_bf16 v[104:107], v[138:141], v[190:193], v[104:107]
	v_mfma_f32_16x16x32_bf16 v[96:99], v[146:149], v[190:193], v[96:99]
	v_mfma_f32_16x16x32_bf16 v[88:91], v[138:141], v[198:201], v[88:91]
	v_mfma_f32_16x16x32_bf16 v[80:83], v[146:149], v[198:201], v[80:83]
	s_setprio 0
	s_barrier
	s_add_i32 s71, 0, 0x14000
	v_add_u32_e32 v166, s71, v170
	s_add_i32 s38, s70, s49
	ds_read_b128 v[202:205], v166
	ds_read_b128 v[206:209], v166 offset:1024
	ds_read_b128 v[210:213], v166 offset:2048
	ds_read_b128 v[214:217], v166 offset:3072
	v_lshl_add_u64 v[166:167], s[42:43], 0, v[176:177]
	s_mov_b32 m0, s38
	v_lshl_add_u64 v[218:219], s[42:43], 0, v[132:133]
	global_load_lds_dwordx4 v[166:167], off
	s_add_i32 m0, s38, 0x2000
	s_nop 0
	global_load_lds_dwordx4 v[218:219], off
	s_barrier
	s_waitcnt lgkmcnt(0)
	s_setprio 1
	s_waitcnt lgkmcnt(0)
	v_mfma_f32_16x16x32_bf16 v[108:111], v[202:205], v[150:153], v[108:111]
	v_mfma_f32_16x16x32_bf16 v[100:103], v[210:213], v[150:153], v[100:103]
	v_mfma_f32_16x16x32_bf16 v[92:95], v[202:205], v[158:161], v[92:95]
	v_mfma_f32_16x16x32_bf16 v[84:87], v[210:213], v[158:161], v[84:87]
	v_mfma_f32_16x16x32_bf16 v[76:79], v[202:205], v[172:175], v[76:79]
	v_mfma_f32_16x16x32_bf16 v[72:75], v[210:213], v[172:175], v[72:75]
	v_mfma_f32_16x16x32_bf16 v[68:71], v[202:205], v[194:197], v[68:71]
	v_mfma_f32_16x16x32_bf16 v[64:67], v[210:213], v[194:197], v[64:67]
	v_mfma_f32_16x16x32_bf16 v[108:111], v[206:209], v[154:157], v[108:111]
	v_mfma_f32_16x16x32_bf16 v[100:103], v[214:217], v[154:157], v[100:103]
	v_mfma_f32_16x16x32_bf16 v[92:95], v[206:209], v[162:165], v[92:95]
	v_mfma_f32_16x16x32_bf16 v[84:87], v[214:217], v[162:165], v[84:87]
	v_mfma_f32_16x16x32_bf16 v[76:79], v[206:209], v[190:193], v[76:79]
	v_mfma_f32_16x16x32_bf16 v[72:75], v[214:217], v[190:193], v[72:75]
	v_mfma_f32_16x16x32_bf16 v[68:71], v[206:209], v[198:201], v[68:71]
	v_mfma_f32_16x16x32_bf16 v[64:67], v[214:217], v[198:201], v[64:67]
	s_setprio 0
	s_mov_b32 m0, s51
	v_lshl_add_u64 v[220:221], s[44:45], 0, v[176:177]
	s_barrier
	ds_read_b128 v[150:153], v171 offset:16384
	ds_read_b128 v[154:157], v171 offset:17408
	ds_read_b128 v[158:161], v171 offset:18432
	ds_read_b128 v[162:165], v171 offset:19456
	ds_read_b128 v[172:175], v171 offset:20480
	ds_read_b128 v[190:193], v171 offset:21504
	ds_read_b128 v[194:197], v171 offset:22528
	ds_read_b128 v[198:201], v171 offset:23552
	global_load_lds_dwordx4 v[220:221], off
	v_lshl_add_u64 v[222:223], s[44:45], 0, v[132:133]
	s_mov_b32 m0, s52
	s_nop 0
	global_load_lds_dwordx4 v[222:223], off
	s_barrier
	s_waitcnt lgkmcnt(0)
	s_setprio 1
	s_waitcnt lgkmcnt(0)
	v_mfma_f32_16x16x32_bf16 v[60:63], v[128:131], v[150:153], v[60:63]
	v_mfma_f32_16x16x32_bf16 v[56:59], v[142:145], v[150:153], v[56:59]
	v_mfma_f32_16x16x32_bf16 v[52:55], v[128:131], v[158:161], v[52:55]
	v_mfma_f32_16x16x32_bf16 v[48:51], v[142:145], v[158:161], v[48:51]
	v_mfma_f32_16x16x32_bf16 v[40:43], v[128:131], v[172:175], v[40:43]
	v_mfma_f32_16x16x32_bf16 v[32:35], v[142:145], v[172:175], v[32:35]
	v_mfma_f32_16x16x32_bf16 v[24:27], v[128:131], v[194:197], v[24:27]
	v_mfma_f32_16x16x32_bf16 v[16:19], v[142:145], v[194:197], v[16:19]
	v_mfma_f32_16x16x32_bf16 v[60:63], v[138:141], v[154:157], v[60:63]
	v_mfma_f32_16x16x32_bf16 v[56:59], v[146:149], v[154:157], v[56:59]
	v_mfma_f32_16x16x32_bf16 v[52:55], v[138:141], v[162:165], v[52:55]
	v_mfma_f32_16x16x32_bf16 v[48:51], v[146:149], v[162:165], v[48:51]
	v_mfma_f32_16x16x32_bf16 v[40:43], v[138:141], v[190:193], v[40:43]
	v_mfma_f32_16x16x32_bf16 v[32:35], v[146:149], v[190:193], v[32:35]
	v_mfma_f32_16x16x32_bf16 v[24:27], v[138:141], v[198:201], v[24:27]
	v_mfma_f32_16x16x32_bf16 v[16:19], v[146:149], v[198:201], v[16:19]
	s_setprio 0
	s_barrier
	s_add_u32 s38, s42, 0x40000
	s_addc_u32 s39, s43, 0
	s_add_i32 s70, s71, s49
	v_lshl_add_u64 v[128:129], s[38:39], 0, v[176:177]
	s_mov_b32 m0, s70
	s_nop 0
	global_load_lds_dwordx4 v[128:129], off
	v_lshl_add_u64 v[128:129], s[38:39], 0, v[132:133]
	s_add_i32 m0, s70, 0x2000
	s_nop 0
	global_load_lds_dwordx4 v[128:129], off
	s_waitcnt vmcnt(6)
	s_barrier
	s_setprio 1
	v_mfma_f32_16x16x32_bf16 v[44:47], v[202:205], v[150:153], v[44:47]
	v_mfma_f32_16x16x32_bf16 v[36:39], v[210:213], v[150:153], v[36:39]
	v_mfma_f32_16x16x32_bf16 v[28:31], v[202:205], v[158:161], v[28:31]
	v_mfma_f32_16x16x32_bf16 v[20:23], v[210:213], v[158:161], v[20:23]
	v_mfma_f32_16x16x32_bf16 v[12:15], v[202:205], v[172:175], v[12:15]
	v_mfma_f32_16x16x32_bf16 v[8:11], v[210:213], v[172:175], v[8:11]
	v_mfma_f32_16x16x32_bf16 v[4:7], v[202:205], v[194:197], v[4:7]
	v_mfma_f32_16x16x32_bf16 v[0:3], v[210:213], v[194:197], v[0:3]
	v_mfma_f32_16x16x32_bf16 v[44:47], v[206:209], v[154:157], v[44:47]
	v_mfma_f32_16x16x32_bf16 v[36:39], v[214:217], v[154:157], v[36:39]
	v_mfma_f32_16x16x32_bf16 v[28:31], v[206:209], v[162:165], v[28:31]
	v_mfma_f32_16x16x32_bf16 v[20:23], v[214:217], v[162:165], v[20:23]
	v_mfma_f32_16x16x32_bf16 v[12:15], v[206:209], v[190:193], v[12:15]
	v_mfma_f32_16x16x32_bf16 v[8:11], v[214:217], v[190:193], v[8:11]
	v_mfma_f32_16x16x32_bf16 v[4:7], v[206:209], v[198:201], v[4:7]
	v_mfma_f32_16x16x32_bf16 v[0:3], v[214:217], v[198:201], v[0:3]
	s_setprio 0
	s_add_i32 s70, 0, 0x18000
	v_add_u32_e32 v146, s70, v170
	s_barrier
	ds_read_b128 v[128:131], v146
	ds_read_b128 v[138:141], v146 offset:1024
	ds_read_b128 v[142:145], v146 offset:2048
	ds_read_b128 v[146:149], v146 offset:3072
	s_add_u32 s38, s44, 0x40000
	s_addc_u32 s39, s45, 0
	s_mov_b32 m0, s53
	v_lshl_add_u64 v[202:203], s[38:39], 0, v[176:177]
	ds_read_b128 v[150:153], v171 offset:32768
	ds_read_b128 v[154:157], v171 offset:33792
	ds_read_b128 v[158:161], v171 offset:34816
	ds_read_b128 v[162:165], v171 offset:35840
	ds_read_b128 v[172:175], v171 offset:36864
	ds_read_b128 v[190:193], v171 offset:37888
	ds_read_b128 v[194:197], v171 offset:38912
	ds_read_b128 v[198:201], v171 offset:39936
	global_load_lds_dwordx4 v[202:203], off
	v_lshl_add_u64 v[202:203], s[38:39], 0, v[132:133]
	s_mov_b32 m0, s54
	s_nop 0
	global_load_lds_dwordx4 v[202:203], off
	s_waitcnt lgkmcnt(8)
	s_barrier
	s_waitcnt lgkmcnt(0)
	s_setprio 1
	s_waitcnt lgkmcnt(0)
	v_mfma_f32_16x16x32_bf16 v[124:127], v[128:131], v[150:153], v[124:127]
	v_mfma_f32_16x16x32_bf16 v[120:123], v[142:145], v[150:153], v[120:123]
	v_mfma_f32_16x16x32_bf16 v[116:119], v[128:131], v[158:161], v[116:119]
	v_mfma_f32_16x16x32_bf16 v[112:115], v[142:145], v[158:161], v[112:115]
	v_mfma_f32_16x16x32_bf16 v[104:107], v[128:131], v[172:175], v[104:107]
	v_mfma_f32_16x16x32_bf16 v[96:99], v[142:145], v[172:175], v[96:99]
	v_mfma_f32_16x16x32_bf16 v[88:91], v[128:131], v[194:197], v[88:91]
	v_mfma_f32_16x16x32_bf16 v[80:83], v[142:145], v[194:197], v[80:83]
	v_mfma_f32_16x16x32_bf16 v[124:127], v[138:141], v[154:157], v[124:127]
	v_mfma_f32_16x16x32_bf16 v[120:123], v[146:149], v[154:157], v[120:123]
	v_mfma_f32_16x16x32_bf16 v[116:119], v[138:141], v[162:165], v[116:119]
	v_mfma_f32_16x16x32_bf16 v[112:115], v[146:149], v[162:165], v[112:115]
	v_mfma_f32_16x16x32_bf16 v[104:107], v[138:141], v[190:193], v[104:107]
	v_mfma_f32_16x16x32_bf16 v[96:99], v[146:149], v[190:193], v[96:99]
	v_mfma_f32_16x16x32_bf16 v[88:91], v[138:141], v[198:201], v[88:91]
	v_mfma_f32_16x16x32_bf16 v[80:83], v[146:149], v[198:201], v[80:83]
	s_setprio 0
	s_barrier
	s_add_i32 s44, 0, 0x1c000
	s_add_i32 s38, s70, s49
	v_add_u32_e32 v214, s44, v170
	v_lshl_add_u64 v[166:167], v[166:167], 0, s[24:25]
	s_mov_b32 m0, s38
	ds_read_b128 v[202:205], v214
	ds_read_b128 v[206:209], v214 offset:1024
	ds_read_b128 v[210:213], v214 offset:2048
	ds_read_b128 v[214:217], v214 offset:3072
	global_load_lds_dwordx4 v[166:167], off
	v_lshl_add_u64 v[166:167], v[218:219], 0, s[24:25]
	s_add_i32 m0, s38, 0x2000
	s_nop 0
	global_load_lds_dwordx4 v[166:167], off
	s_barrier
	s_waitcnt lgkmcnt(0)
	s_setprio 1
	s_waitcnt lgkmcnt(0)
	v_mfma_f32_16x16x32_bf16 v[108:111], v[202:205], v[150:153], v[108:111]
	v_mfma_f32_16x16x32_bf16 v[100:103], v[210:213], v[150:153], v[100:103]
	v_mfma_f32_16x16x32_bf16 v[92:95], v[202:205], v[158:161], v[92:95]
	v_mfma_f32_16x16x32_bf16 v[84:87], v[210:213], v[158:161], v[84:87]
	v_mfma_f32_16x16x32_bf16 v[76:79], v[202:205], v[172:175], v[76:79]
	v_mfma_f32_16x16x32_bf16 v[72:75], v[210:213], v[172:175], v[72:75]
	v_mfma_f32_16x16x32_bf16 v[68:71], v[202:205], v[194:197], v[68:71]
	v_mfma_f32_16x16x32_bf16 v[64:67], v[210:213], v[194:197], v[64:67]
	v_mfma_f32_16x16x32_bf16 v[108:111], v[206:209], v[154:157], v[108:111]
	v_mfma_f32_16x16x32_bf16 v[100:103], v[214:217], v[154:157], v[100:103]
	v_mfma_f32_16x16x32_bf16 v[92:95], v[206:209], v[162:165], v[92:95]
	v_mfma_f32_16x16x32_bf16 v[84:87], v[214:217], v[162:165], v[84:87]
	v_mfma_f32_16x16x32_bf16 v[76:79], v[206:209], v[190:193], v[76:79]
	v_mfma_f32_16x16x32_bf16 v[72:75], v[214:217], v[190:193], v[72:75]
	v_mfma_f32_16x16x32_bf16 v[68:71], v[206:209], v[198:201], v[68:71]
	v_mfma_f32_16x16x32_bf16 v[64:67], v[214:217], v[198:201], v[64:67]
	s_setprio 0
	s_mov_b32 m0, s56
	v_lshl_add_u64 v[166:167], v[220:221], 0, s[24:25]
	s_barrier
	ds_read_b128 v[150:153], v171 offset:49152
	ds_read_b128 v[154:157], v171 offset:50176
	ds_read_b128 v[158:161], v171 offset:51200
	ds_read_b128 v[162:165], v171 offset:52224
	ds_read_b128 v[172:175], v171 offset:53248
	ds_read_b128 v[190:193], v171 offset:54272
	ds_read_b128 v[194:197], v171 offset:55296
	ds_read_b128 v[198:201], v171 offset:56320
	global_load_lds_dwordx4 v[166:167], off
	v_lshl_add_u64 v[166:167], v[222:223], 0, s[24:25]
	s_mov_b32 m0, s57
	s_nop 0
	global_load_lds_dwordx4 v[166:167], off
	s_barrier
	s_waitcnt lgkmcnt(0)
	s_setprio 1
	s_waitcnt lgkmcnt(0)
	v_mfma_f32_16x16x32_bf16 v[60:63], v[128:131], v[150:153], v[60:63]
	v_mfma_f32_16x16x32_bf16 v[56:59], v[142:145], v[150:153], v[56:59]
	v_mfma_f32_16x16x32_bf16 v[52:55], v[128:131], v[158:161], v[52:55]
	v_mfma_f32_16x16x32_bf16 v[48:51], v[142:145], v[158:161], v[48:51]
	v_mfma_f32_16x16x32_bf16 v[40:43], v[128:131], v[172:175], v[40:43]
	v_mfma_f32_16x16x32_bf16 v[32:35], v[142:145], v[172:175], v[32:35]
	v_mfma_f32_16x16x32_bf16 v[24:27], v[128:131], v[194:197], v[24:27]
	v_mfma_f32_16x16x32_bf16 v[16:19], v[142:145], v[194:197], v[16:19]
	v_mfma_f32_16x16x32_bf16 v[60:63], v[138:141], v[154:157], v[60:63]
	v_mfma_f32_16x16x32_bf16 v[56:59], v[146:149], v[154:157], v[56:59]
	v_mfma_f32_16x16x32_bf16 v[52:55], v[138:141], v[162:165], v[52:55]
	v_mfma_f32_16x16x32_bf16 v[48:51], v[146:149], v[162:165], v[48:51]
	v_mfma_f32_16x16x32_bf16 v[40:43], v[138:141], v[190:193], v[40:43]
	v_mfma_f32_16x16x32_bf16 v[32:35], v[146:149], v[190:193], v[32:35]
	v_mfma_f32_16x16x32_bf16 v[24:27], v[138:141], v[198:201], v[24:27]
	v_mfma_f32_16x16x32_bf16 v[16:19], v[146:149], v[198:201], v[16:19]
	s_setprio 0
	s_barrier
	s_add_u32 s38, s42, 0x40080
	s_addc_u32 s39, s43, 0
	s_add_i32 s42, s44, s49
	v_lshl_add_u64 v[128:129], s[38:39], 0, v[176:177]
	s_mov_b32 m0, s42
	s_nop 0
	global_load_lds_dwordx4 v[128:129], off
	v_lshl_add_u64 v[128:129], s[38:39], 0, v[132:133]
	s_add_i32 m0, s42, 0x2000
	s_nop 0
	global_load_lds_dwordx4 v[128:129], off
	s_waitcnt vmcnt(6)
	s_barrier
	s_setprio 1
	v_mfma_f32_16x16x32_bf16 v[44:47], v[202:205], v[150:153], v[44:47]
	v_mfma_f32_16x16x32_bf16 v[36:39], v[210:213], v[150:153], v[36:39]
	v_mfma_f32_16x16x32_bf16 v[28:31], v[202:205], v[158:161], v[28:31]
	v_mfma_f32_16x16x32_bf16 v[20:23], v[210:213], v[158:161], v[20:23]
	v_mfma_f32_16x16x32_bf16 v[12:15], v[202:205], v[172:175], v[12:15]
	v_mfma_f32_16x16x32_bf16 v[8:11], v[210:213], v[172:175], v[8:11]
	v_mfma_f32_16x16x32_bf16 v[4:7], v[202:205], v[194:197], v[4:7]
	v_mfma_f32_16x16x32_bf16 v[0:3], v[210:213], v[194:197], v[0:3]
	v_mfma_f32_16x16x32_bf16 v[44:47], v[206:209], v[154:157], v[44:47]
	v_mfma_f32_16x16x32_bf16 v[36:39], v[214:217], v[154:157], v[36:39]
	v_mfma_f32_16x16x32_bf16 v[28:31], v[206:209], v[162:165], v[28:31]
	v_mfma_f32_16x16x32_bf16 v[20:23], v[214:217], v[162:165], v[20:23]
	v_mfma_f32_16x16x32_bf16 v[12:15], v[206:209], v[190:193], v[12:15]
	v_mfma_f32_16x16x32_bf16 v[8:11], v[214:217], v[190:193], v[8:11]
	v_mfma_f32_16x16x32_bf16 v[4:7], v[206:209], v[198:201], v[4:7]
	v_mfma_f32_16x16x32_bf16 v[0:3], v[214:217], v[198:201], v[0:3]
	s_setprio 0
	s_add_u32 s67, s67, 0x100
	s_addc_u32 s68, s68, 0
	s_cmp_ge_i32 s69, s63
	s_mov_b64 s[38:39], s[40:41]
	s_mov_b32 s42, s69
	s_barrier
	s_cbranch_scc0 .LBB0_1322
	v_mov_b32_e32 v166, v169
	s_mov_b32 s13, s55
	v_mov_b32_e32 v128, v168
	s_mov_b32 s23, s48
	s_lshl_b32 s22, s22, 8
	s_lshl_b32 s23, s23, 6
	s_add_i32 s23, s23, s22
	s_lshl_b32 s22, s62, 8
	s_lshl_b32 s13, s13, 5
	s_add_i32 s13, s13, s22
	v_lshl_add_u32 v140, v166, 2, s13
	v_add_u32_e32 v138, s23, v128
	s_mov_b64 s[22:23], -1
	s_cmp_gt_i32 s47, 0
	v_ashrrev_i32_e32 v141, 31, v140
	s_cbranch_scc1 .LBB0_1474
	v_lshlrev_b32_e32 v139, 11, v138
	v_lshl_add_u32 v139, v140, 1, v139
	v_lshlrev_b32_e32 v143, 2, v138
	v_xor_b32_e32 v238, 16, v229
	v_xor_b32_e32 v239, 32, v229
	v_lshlrev_b32_e32 v238, 2, v238
	v_lshlrev_b32_e32 v239, 2, v239
	v_mov_b32_e32 v142, v139
	s_and_b64 vcc, exec, s[6:7]
	s_cbranch_vccnz .LresF_xin
	v_mov_b32_e32 v141, v139
	global_load_dwordx2 v[192:193], v141, s[96:97]
	global_load_dwordx2 v[194:195], v141, s[96:97] offset:32
	global_load_dwordx2 v[196:197], v141, s[96:97] offset:256
	global_load_dwordx2 v[198:199], v141, s[96:97] offset:288
	v_add_u32_e32 v141, 0x8000, v141
	global_load_dwordx2 v[200:201], v141, s[96:97]
	global_load_dwordx2 v[202:203], v141, s[96:97] offset:32
	global_load_dwordx2 v[204:205], v141, s[96:97] offset:256
	global_load_dwordx2 v[206:207], v141, s[96:97] offset:288
	v_add_u32_e32 v141, 0x8000, v141
	global_load_dwordx2 v[208:209], v141, s[96:97]
	global_load_dwordx2 v[210:211], v141, s[96:97] offset:32
	global_load_dwordx2 v[212:213], v141, s[96:97] offset:256
	global_load_dwordx2 v[214:215], v141, s[96:97] offset:288
	v_add_u32_e32 v141, 0x8000, v141
	global_load_dwordx2 v[216:217], v141, s[96:97]
	global_load_dwordx2 v[218:219], v141, s[96:97] offset:32
	global_load_dwordx2 v[220:221], v141, s[96:97] offset:256
	global_load_dwordx2 v[222:223], v141, s[96:97] offset:288
	v_add_u32_e32 v141, 0x28000, v141
	global_load_dwordx2 v[144:145], v141, s[96:97]
	global_load_dwordx2 v[146:147], v141, s[96:97] offset:32
	global_load_dwordx2 v[148:149], v141, s[96:97] offset:256
	global_load_dwordx2 v[150:151], v141, s[96:97] offset:288
	v_add_u32_e32 v141, 0x8000, v141
	global_load_dwordx2 v[152:153], v141, s[96:97]
	global_load_dwordx2 v[154:155], v141, s[96:97] offset:32
	global_load_dwordx2 v[156:157], v141, s[96:97] offset:256
	global_load_dwordx2 v[158:159], v141, s[96:97] offset:288
	v_add_u32_e32 v141, 0x8000, v141
	global_load_dwordx2 v[160:161], v141, s[96:97]
	global_load_dwordx2 v[162:163], v141, s[96:97] offset:32
	global_load_dwordx2 v[164:165], v141, s[96:97] offset:256
	global_load_dwordx2 v[166:167], v141, s[96:97] offset:288
	v_add_u32_e32 v141, 0x8000, v141
	global_load_dwordx2 v[240:241], v141, s[96:97]
	global_load_dwordx2 v[242:243], v141, s[96:97] offset:32
	global_load_dwordx2 v[244:245], v141, s[96:97] offset:256
	global_load_dwordx2 v[246:247], v141, s[96:97] offset:288
	s_waitcnt vmcnt(31)
	v_lshlrev_b32_e32 v252, 16, v192
	v_and_b32_e32 v253, 0xffff0000, v192
	v_lshlrev_b32_e32 v254, 16, v193
	v_and_b32_e32 v255, 0xffff0000, v193
	v_pk_add_f32 v[252:253], v[124:125], v[252:253]
	v_pk_add_f32 v[254:255], v[126:127], v[254:255]
	v_mul_f32_e32 v128, v252, v252
	v_fmac_f32_e32 v128, v253, v253
	v_fmac_f32_e32 v128, v254, v254
	v_fmac_f32_e32 v128, v255, v255
	v_cvt_pk_bf16_f32 v190, v252, v253
	v_cvt_pk_bf16_f32 v191, v254, v255
	global_store_dwordx2 v142, v[190:191], s[96:97]
	s_waitcnt vmcnt(31)
	v_lshlrev_b32_e32 v252, 16, v194
	v_and_b32_e32 v253, 0xffff0000, v194
	v_lshlrev_b32_e32 v254, 16, v195
	v_and_b32_e32 v255, 0xffff0000, v195
	v_pk_add_f32 v[252:253], v[120:121], v[252:253]
	v_pk_add_f32 v[254:255], v[122:123], v[254:255]
	v_fmac_f32_e32 v128, v252, v252
	v_fmac_f32_e32 v128, v253, v253
	v_fmac_f32_e32 v128, v254, v254
	v_fmac_f32_e32 v128, v255, v255
	v_cvt_pk_bf16_f32 v190, v252, v253
	v_cvt_pk_bf16_f32 v191, v254, v255
	global_store_dwordx2 v142, v[190:191], s[96:97] offset:32
	s_waitcnt vmcnt(31)
	v_lshlrev_b32_e32 v252, 16, v196
	v_and_b32_e32 v253, 0xffff0000, v196
	v_lshlrev_b32_e32 v254, 16, v197
	v_and_b32_e32 v255, 0xffff0000, v197
	v_pk_add_f32 v[252:253], v[108:109], v[252:253]
	v_pk_add_f32 v[254:255], v[110:111], v[254:255]
	v_fmac_f32_e32 v128, v252, v252
	v_fmac_f32_e32 v128, v253, v253
	v_fmac_f32_e32 v128, v254, v254
	v_fmac_f32_e32 v128, v255, v255
	v_cvt_pk_bf16_f32 v190, v252, v253
	v_cvt_pk_bf16_f32 v191, v254, v255
	global_store_dwordx2 v142, v[190:191], s[96:97] offset:256
	s_waitcnt vmcnt(31)
	v_lshlrev_b32_e32 v252, 16, v198
	v_and_b32_e32 v253, 0xffff0000, v198
	v_lshlrev_b32_e32 v254, 16, v199
	v_and_b32_e32 v255, 0xffff0000, v199
	v_pk_add_f32 v[252:253], v[100:101], v[252:253]
	v_pk_add_f32 v[254:255], v[102:103], v[254:255]
	v_fmac_f32_e32 v128, v252, v252
	v_fmac_f32_e32 v128, v253, v253
	v_fmac_f32_e32 v128, v254, v254
	v_fmac_f32_e32 v128, v255, v255
	v_cvt_pk_bf16_f32 v190, v252, v253
	v_cvt_pk_bf16_f32 v191, v254, v255
	global_store_dwordx2 v142, v[190:191], s[96:97] offset:288
	v_add_u32_e32 v142, 0x8000, v142
	s_waitcnt vmcnt(31)
	v_lshlrev_b32_e32 v252, 16, v200
	v_and_b32_e32 v253, 0xffff0000, v200
	v_lshlrev_b32_e32 v254, 16, v201
	v_and_b32_e32 v255, 0xffff0000, v201
	v_pk_add_f32 v[252:253], v[116:117], v[252:253]
	v_pk_add_f32 v[254:255], v[118:119], v[254:255]
	v_mul_f32_e32 v129, v252, v252
	v_fmac_f32_e32 v129, v253, v253
	v_fmac_f32_e32 v129, v254, v254
	v_fmac_f32_e32 v129, v255, v255
	v_cvt_pk_bf16_f32 v190, v252, v253
	v_cvt_pk_bf16_f32 v191, v254, v255
	global_store_dwordx2 v142, v[190:191], s[96:97]
	s_waitcnt vmcnt(31)
	v_lshlrev_b32_e32 v252, 16, v202
	v_and_b32_e32 v253, 0xffff0000, v202
	v_lshlrev_b32_e32 v254, 16, v203
	v_and_b32_e32 v255, 0xffff0000, v203
	v_pk_add_f32 v[252:253], v[112:113], v[252:253]
	v_pk_add_f32 v[254:255], v[114:115], v[254:255]
	v_fmac_f32_e32 v129, v252, v252
	v_fmac_f32_e32 v129, v253, v253
	v_fmac_f32_e32 v129, v254, v254
	v_fmac_f32_e32 v129, v255, v255
	v_cvt_pk_bf16_f32 v190, v252, v253
	v_cvt_pk_bf16_f32 v191, v254, v255
	global_store_dwordx2 v142, v[190:191], s[96:97] offset:32
	s_waitcnt vmcnt(31)
	v_lshlrev_b32_e32 v252, 16, v204
	v_and_b32_e32 v253, 0xffff0000, v204
	v_lshlrev_b32_e32 v254, 16, v205
	v_and_b32_e32 v255, 0xffff0000, v205
	v_pk_add_f32 v[252:253], v[92:93], v[252:253]
	v_pk_add_f32 v[254:255], v[94:95], v[254:255]
	v_fmac_f32_e32 v129, v252, v252
	v_fmac_f32_e32 v129, v253, v253
	v_fmac_f32_e32 v129, v254, v254
	v_fmac_f32_e32 v129, v255, v255
	v_cvt_pk_bf16_f32 v190, v252, v253
	v_cvt_pk_bf16_f32 v191, v254, v255
	global_store_dwordx2 v142, v[190:191], s[96:97] offset:256
	s_waitcnt vmcnt(31)
	v_lshlrev_b32_e32 v252, 16, v206
	v_and_b32_e32 v253, 0xffff0000, v206
	v_lshlrev_b32_e32 v254, 16, v207
	v_and_b32_e32 v255, 0xffff0000, v207
	v_pk_add_f32 v[252:253], v[84:85], v[252:253]
	v_pk_add_f32 v[254:255], v[86:87], v[254:255]
	v_fmac_f32_e32 v129, v252, v252
	v_fmac_f32_e32 v129, v253, v253
	v_fmac_f32_e32 v129, v254, v254
	v_fmac_f32_e32 v129, v255, v255
	v_cvt_pk_bf16_f32 v190, v252, v253
	v_cvt_pk_bf16_f32 v191, v254, v255
	global_store_dwordx2 v142, v[190:191], s[96:97] offset:288
	v_add_u32_e32 v142, 0x8000, v142
	s_waitcnt vmcnt(31)
	v_lshlrev_b32_e32 v252, 16, v208
	v_and_b32_e32 v253, 0xffff0000, v208
	v_lshlrev_b32_e32 v254, 16, v209
	v_and_b32_e32 v255, 0xffff0000, v209
	v_pk_add_f32 v[252:253], v[104:105], v[252:253]
	v_pk_add_f32 v[254:255], v[106:107], v[254:255]
	v_mul_f32_e32 v130, v252, v252
	v_fmac_f32_e32 v130, v253, v253
	v_fmac_f32_e32 v130, v254, v254
	v_fmac_f32_e32 v130, v255, v255
	v_cvt_pk_bf16_f32 v190, v252, v253
	v_cvt_pk_bf16_f32 v191, v254, v255
	global_store_dwordx2 v142, v[190:191], s[96:97]
	s_waitcnt vmcnt(31)
	v_lshlrev_b32_e32 v252, 16, v210
	v_and_b32_e32 v253, 0xffff0000, v210
	v_lshlrev_b32_e32 v254, 16, v211
	v_and_b32_e32 v255, 0xffff0000, v211
	v_pk_add_f32 v[252:253], v[96:97], v[252:253]
	v_pk_add_f32 v[254:255], v[98:99], v[254:255]
	v_fmac_f32_e32 v130, v252, v252
	v_fmac_f32_e32 v130, v253, v253
	v_fmac_f32_e32 v130, v254, v254
	v_fmac_f32_e32 v130, v255, v255
	v_cvt_pk_bf16_f32 v190, v252, v253
	v_cvt_pk_bf16_f32 v191, v254, v255
	global_store_dwordx2 v142, v[190:191], s[96:97] offset:32
	s_waitcnt vmcnt(31)
	v_lshlrev_b32_e32 v252, 16, v212
	v_and_b32_e32 v253, 0xffff0000, v212
	v_lshlrev_b32_e32 v254, 16, v213
	v_and_b32_e32 v255, 0xffff0000, v213
	v_pk_add_f32 v[252:253], v[76:77], v[252:253]
	v_pk_add_f32 v[254:255], v[78:79], v[254:255]
	v_fmac_f32_e32 v130, v252, v252
	v_fmac_f32_e32 v130, v253, v253
	v_fmac_f32_e32 v130, v254, v254
	v_fmac_f32_e32 v130, v255, v255
	v_cvt_pk_bf16_f32 v190, v252, v253
	v_cvt_pk_bf16_f32 v191, v254, v255
	global_store_dwordx2 v142, v[190:191], s[96:97] offset:256
	s_waitcnt vmcnt(31)
	v_lshlrev_b32_e32 v252, 16, v214
	v_and_b32_e32 v253, 0xffff0000, v214
	v_lshlrev_b32_e32 v254, 16, v215
	v_and_b32_e32 v255, 0xffff0000, v215
	v_pk_add_f32 v[252:253], v[72:73], v[252:253]
	v_pk_add_f32 v[254:255], v[74:75], v[254:255]
	v_fmac_f32_e32 v130, v252, v252
	v_fmac_f32_e32 v130, v253, v253
	v_fmac_f32_e32 v130, v254, v254
	v_fmac_f32_e32 v130, v255, v255
	v_cvt_pk_bf16_f32 v190, v252, v253
	v_cvt_pk_bf16_f32 v191, v254, v255
	global_store_dwordx2 v142, v[190:191], s[96:97] offset:288
	v_add_u32_e32 v142, 0x8000, v142
	s_waitcnt vmcnt(31)
	v_lshlrev_b32_e32 v252, 16, v216
	v_and_b32_e32 v253, 0xffff0000, v216
	v_lshlrev_b32_e32 v254, 16, v217
	v_and_b32_e32 v255, 0xffff0000, v217
	v_pk_add_f32 v[252:253], v[88:89], v[252:253]
	v_pk_add_f32 v[254:255], v[90:91], v[254:255]
	v_mul_f32_e32 v131, v252, v252
	v_fmac_f32_e32 v131, v253, v253
	v_fmac_f32_e32 v131, v254, v254
	v_fmac_f32_e32 v131, v255, v255
	v_cvt_pk_bf16_f32 v190, v252, v253
	v_cvt_pk_bf16_f32 v191, v254, v255
	global_store_dwordx2 v142, v[190:191], s[96:97]
	s_waitcnt vmcnt(31)
	v_lshlrev_b32_e32 v252, 16, v218
	v_and_b32_e32 v253, 0xffff0000, v218
	v_lshlrev_b32_e32 v254, 16, v219
	v_and_b32_e32 v255, 0xffff0000, v219
	v_pk_add_f32 v[252:253], v[80:81], v[252:253]
	v_pk_add_f32 v[254:255], v[82:83], v[254:255]
	v_fmac_f32_e32 v131, v252, v252
	v_fmac_f32_e32 v131, v253, v253
	v_fmac_f32_e32 v131, v254, v254
	v_fmac_f32_e32 v131, v255, v255
	v_cvt_pk_bf16_f32 v190, v252, v253
	v_cvt_pk_bf16_f32 v191, v254, v255
	global_store_dwordx2 v142, v[190:191], s[96:97] offset:32
	s_waitcnt vmcnt(31)
	v_lshlrev_b32_e32 v252, 16, v220
	v_and_b32_e32 v253, 0xffff0000, v220
	v_lshlrev_b32_e32 v254, 16, v221
	v_and_b32_e32 v255, 0xffff0000, v221
	v_pk_add_f32 v[252:253], v[68:69], v[252:253]
	v_pk_add_f32 v[254:255], v[70:71], v[254:255]
	v_fmac_f32_e32 v131, v252, v252
	v_fmac_f32_e32 v131, v253, v253
	v_fmac_f32_e32 v131, v254, v254
	v_fmac_f32_e32 v131, v255, v255
	v_cvt_pk_bf16_f32 v190, v252, v253
	v_cvt_pk_bf16_f32 v191, v254, v255
	global_store_dwordx2 v142, v[190:191], s[96:97] offset:256
	s_waitcnt vmcnt(31)
	v_lshlrev_b32_e32 v252, 16, v222
	v_and_b32_e32 v253, 0xffff0000, v222
	v_lshlrev_b32_e32 v254, 16, v223
	v_and_b32_e32 v255, 0xffff0000, v223
	v_pk_add_f32 v[252:253], v[64:65], v[252:253]
	v_pk_add_f32 v[254:255], v[66:67], v[254:255]
	v_fmac_f32_e32 v131, v252, v252
	v_fmac_f32_e32 v131, v253, v253
	v_fmac_f32_e32 v131, v254, v254
	v_fmac_f32_e32 v131, v255, v255
	v_cvt_pk_bf16_f32 v190, v252, v253
	v_cvt_pk_bf16_f32 v191, v254, v255
	global_store_dwordx2 v142, v[190:191], s[96:97] offset:288
	v_add_u32_e32 v142, 0x28000, v142
	s_waitcnt vmcnt(31)
	v_lshlrev_b32_e32 v252, 16, v144
	v_and_b32_e32 v253, 0xffff0000, v144
	v_lshlrev_b32_e32 v254, 16, v145
	v_and_b32_e32 v255, 0xffff0000, v145
	v_pk_add_f32 v[252:253], v[60:61], v[252:253]
	v_pk_add_f32 v[254:255], v[62:63], v[254:255]
	v_mul_f32_e32 v172, v252, v252
	v_fmac_f32_e32 v172, v253, v253
	v_fmac_f32_e32 v172, v254, v254
	v_fmac_f32_e32 v172, v255, v255
	v_cvt_pk_bf16_f32 v190, v252, v253
	v_cvt_pk_bf16_f32 v191, v254, v255
	global_store_dwordx2 v142, v[190:191], s[96:97]
	s_waitcnt vmcnt(31)
	v_lshlrev_b32_e32 v252, 16, v146
	v_and_b32_e32 v253, 0xffff0000, v146
	v_lshlrev_b32_e32 v254, 16, v147
	v_and_b32_e32 v255, 0xffff0000, v147
	v_pk_add_f32 v[252:253], v[56:57], v[252:253]
	v_pk_add_f32 v[254:255], v[58:59], v[254:255]
	v_fmac_f32_e32 v172, v252, v252
	v_fmac_f32_e32 v172, v253, v253
	v_fmac_f32_e32 v172, v254, v254
	v_fmac_f32_e32 v172, v255, v255
	v_cvt_pk_bf16_f32 v190, v252, v253
	v_cvt_pk_bf16_f32 v191, v254, v255
	global_store_dwordx2 v142, v[190:191], s[96:97] offset:32
	s_waitcnt vmcnt(31)
	v_lshlrev_b32_e32 v252, 16, v148
	v_and_b32_e32 v253, 0xffff0000, v148
	v_lshlrev_b32_e32 v254, 16, v149
	v_and_b32_e32 v255, 0xffff0000, v149
	v_pk_add_f32 v[252:253], v[44:45], v[252:253]
	v_pk_add_f32 v[254:255], v[46:47], v[254:255]
	v_fmac_f32_e32 v172, v252, v252
	v_fmac_f32_e32 v172, v253, v253
	v_fmac_f32_e32 v172, v254, v254
	v_fmac_f32_e32 v172, v255, v255
	v_cvt_pk_bf16_f32 v190, v252, v253
	v_cvt_pk_bf16_f32 v191, v254, v255
	global_store_dwordx2 v142, v[190:191], s[96:97] offset:256
	s_waitcnt vmcnt(31)
	v_lshlrev_b32_e32 v252, 16, v150
	v_and_b32_e32 v253, 0xffff0000, v150
	v_lshlrev_b32_e32 v254, 16, v151
	v_and_b32_e32 v255, 0xffff0000, v151
	v_pk_add_f32 v[252:253], v[36:37], v[252:253]
	v_pk_add_f32 v[254:255], v[38:39], v[254:255]
	v_fmac_f32_e32 v172, v252, v252
	v_fmac_f32_e32 v172, v253, v253
	v_fmac_f32_e32 v172, v254, v254
	v_fmac_f32_e32 v172, v255, v255
	v_cvt_pk_bf16_f32 v190, v252, v253
	v_cvt_pk_bf16_f32 v191, v254, v255
	global_store_dwordx2 v142, v[190:191], s[96:97] offset:288
	v_add_u32_e32 v142, 0x8000, v142
	s_waitcnt vmcnt(31)
	v_lshlrev_b32_e32 v252, 16, v152
	v_and_b32_e32 v253, 0xffff0000, v152
	v_lshlrev_b32_e32 v254, 16, v153
	v_and_b32_e32 v255, 0xffff0000, v153
	v_pk_add_f32 v[252:253], v[52:53], v[252:253]
	v_pk_add_f32 v[254:255], v[54:55], v[254:255]
	v_mul_f32_e32 v173, v252, v252
	v_fmac_f32_e32 v173, v253, v253
	v_fmac_f32_e32 v173, v254, v254
	v_fmac_f32_e32 v173, v255, v255
	v_cvt_pk_bf16_f32 v190, v252, v253
	v_cvt_pk_bf16_f32 v191, v254, v255
	global_store_dwordx2 v142, v[190:191], s[96:97]
	s_waitcnt vmcnt(31)
	v_lshlrev_b32_e32 v252, 16, v154
	v_and_b32_e32 v253, 0xffff0000, v154
	v_lshlrev_b32_e32 v254, 16, v155
	v_and_b32_e32 v255, 0xffff0000, v155
	v_pk_add_f32 v[252:253], v[48:49], v[252:253]
	v_pk_add_f32 v[254:255], v[50:51], v[254:255]
	v_fmac_f32_e32 v173, v252, v252
	v_fmac_f32_e32 v173, v253, v253
	v_fmac_f32_e32 v173, v254, v254
	v_fmac_f32_e32 v173, v255, v255
	v_cvt_pk_bf16_f32 v190, v252, v253
	v_cvt_pk_bf16_f32 v191, v254, v255
	global_store_dwordx2 v142, v[190:191], s[96:97] offset:32
	s_waitcnt vmcnt(31)
	v_lshlrev_b32_e32 v252, 16, v156
	v_and_b32_e32 v253, 0xffff0000, v156
	v_lshlrev_b32_e32 v254, 16, v157
	v_and_b32_e32 v255, 0xffff0000, v157
	v_pk_add_f32 v[252:253], v[28:29], v[252:253]
	v_pk_add_f32 v[254:255], v[30:31], v[254:255]
	v_fmac_f32_e32 v173, v252, v252
	v_fmac_f32_e32 v173, v253, v253
	v_fmac_f32_e32 v173, v254, v254
	v_fmac_f32_e32 v173, v255, v255
	v_cvt_pk_bf16_f32 v190, v252, v253
	v_cvt_pk_bf16_f32 v191, v254, v255
	global_store_dwordx2 v142, v[190:191], s[96:97] offset:256
	s_waitcnt vmcnt(31)
	v_lshlrev_b32_e32 v252, 16, v158
	v_and_b32_e32 v253, 0xffff0000, v158
	v_lshlrev_b32_e32 v254, 16, v159
	v_and_b32_e32 v255, 0xffff0000, v159
	v_pk_add_f32 v[252:253], v[20:21], v[252:253]
	v_pk_add_f32 v[254:255], v[22:23], v[254:255]
	v_fmac_f32_e32 v173, v252, v252
	v_fmac_f32_e32 v173, v253, v253
	v_fmac_f32_e32 v173, v254, v254
	v_fmac_f32_e32 v173, v255, v255
	v_cvt_pk_bf16_f32 v190, v252, v253
	v_cvt_pk_bf16_f32 v191, v254, v255
	global_store_dwordx2 v142, v[190:191], s[96:97] offset:288
	v_add_u32_e32 v142, 0x8000, v142
	s_waitcnt vmcnt(31)
	v_lshlrev_b32_e32 v252, 16, v160
	v_and_b32_e32 v253, 0xffff0000, v160
	v_lshlrev_b32_e32 v254, 16, v161
	v_and_b32_e32 v255, 0xffff0000, v161
	v_pk_add_f32 v[252:253], v[40:41], v[252:253]
	v_pk_add_f32 v[254:255], v[42:43], v[254:255]
	v_mul_f32_e32 v174, v252, v252
	v_fmac_f32_e32 v174, v253, v253
	v_fmac_f32_e32 v174, v254, v254
	v_fmac_f32_e32 v174, v255, v255
	v_cvt_pk_bf16_f32 v190, v252, v253
	v_cvt_pk_bf16_f32 v191, v254, v255
	global_store_dwordx2 v142, v[190:191], s[96:97]
	s_waitcnt vmcnt(31)
	v_lshlrev_b32_e32 v252, 16, v162
	v_and_b32_e32 v253, 0xffff0000, v162
	v_lshlrev_b32_e32 v254, 16, v163
	v_and_b32_e32 v255, 0xffff0000, v163
	v_pk_add_f32 v[252:253], v[32:33], v[252:253]
	v_pk_add_f32 v[254:255], v[34:35], v[254:255]
	v_fmac_f32_e32 v174, v252, v252
	v_fmac_f32_e32 v174, v253, v253
	v_fmac_f32_e32 v174, v254, v254
	v_fmac_f32_e32 v174, v255, v255
	v_cvt_pk_bf16_f32 v190, v252, v253
	v_cvt_pk_bf16_f32 v191, v254, v255
	global_store_dwordx2 v142, v[190:191], s[96:97] offset:32
	s_waitcnt vmcnt(31)
	v_lshlrev_b32_e32 v252, 16, v164
	v_and_b32_e32 v253, 0xffff0000, v164
	v_lshlrev_b32_e32 v254, 16, v165
	v_and_b32_e32 v255, 0xffff0000, v165
	v_pk_add_f32 v[252:253], v[12:13], v[252:253]
	v_pk_add_f32 v[254:255], v[14:15], v[254:255]
	v_fmac_f32_e32 v174, v252, v252
	v_fmac_f32_e32 v174, v253, v253
	v_fmac_f32_e32 v174, v254, v254
	v_fmac_f32_e32 v174, v255, v255
	v_cvt_pk_bf16_f32 v190, v252, v253
	v_cvt_pk_bf16_f32 v191, v254, v255
	global_store_dwordx2 v142, v[190:191], s[96:97] offset:256
	s_waitcnt vmcnt(31)
	v_lshlrev_b32_e32 v252, 16, v166
	v_and_b32_e32 v253, 0xffff0000, v166
	v_lshlrev_b32_e32 v254, 16, v167
	v_and_b32_e32 v255, 0xffff0000, v167
	v_pk_add_f32 v[252:253], v[8:9], v[252:253]
	v_pk_add_f32 v[254:255], v[10:11], v[254:255]
	v_fmac_f32_e32 v174, v252, v252
	v_fmac_f32_e32 v174, v253, v253
	v_fmac_f32_e32 v174, v254, v254
	v_fmac_f32_e32 v174, v255, v255
	v_cvt_pk_bf16_f32 v190, v252, v253
	v_cvt_pk_bf16_f32 v191, v254, v255
	global_store_dwordx2 v142, v[190:191], s[96:97] offset:288
	v_add_u32_e32 v142, 0x8000, v142
	s_waitcnt vmcnt(31)
	v_lshlrev_b32_e32 v252, 16, v240
	v_and_b32_e32 v253, 0xffff0000, v240
	v_lshlrev_b32_e32 v254, 16, v241
	v_and_b32_e32 v255, 0xffff0000, v241
	v_pk_add_f32 v[252:253], v[24:25], v[252:253]
	v_pk_add_f32 v[254:255], v[26:27], v[254:255]
	v_mul_f32_e32 v175, v252, v252
	v_fmac_f32_e32 v175, v253, v253
	v_fmac_f32_e32 v175, v254, v254
	v_fmac_f32_e32 v175, v255, v255
	v_cvt_pk_bf16_f32 v190, v252, v253
	v_cvt_pk_bf16_f32 v191, v254, v255
	global_store_dwordx2 v142, v[190:191], s[96:97]
	s_waitcnt vmcnt(31)
	v_lshlrev_b32_e32 v252, 16, v242
	v_and_b32_e32 v253, 0xffff0000, v242
	v_lshlrev_b32_e32 v254, 16, v243
	v_and_b32_e32 v255, 0xffff0000, v243
	v_pk_add_f32 v[252:253], v[16:17], v[252:253]
	v_pk_add_f32 v[254:255], v[18:19], v[254:255]
	v_fmac_f32_e32 v175, v252, v252
	v_fmac_f32_e32 v175, v253, v253
	v_fmac_f32_e32 v175, v254, v254
	v_fmac_f32_e32 v175, v255, v255
	v_cvt_pk_bf16_f32 v190, v252, v253
	v_cvt_pk_bf16_f32 v191, v254, v255
	global_store_dwordx2 v142, v[190:191], s[96:97] offset:32
	s_waitcnt vmcnt(31)
	v_lshlrev_b32_e32 v252, 16, v244
	v_and_b32_e32 v253, 0xffff0000, v244
	v_lshlrev_b32_e32 v254, 16, v245
	v_and_b32_e32 v255, 0xffff0000, v245
	v_pk_add_f32 v[252:253], v[4:5], v[252:253]
	v_pk_add_f32 v[254:255], v[6:7], v[254:255]
	v_fmac_f32_e32 v175, v252, v252
	v_fmac_f32_e32 v175, v253, v253
	v_fmac_f32_e32 v175, v254, v254
	v_fmac_f32_e32 v175, v255, v255
	v_cvt_pk_bf16_f32 v190, v252, v253
	v_cvt_pk_bf16_f32 v191, v254, v255
	global_store_dwordx2 v142, v[190:191], s[96:97] offset:256
	s_waitcnt vmcnt(31)
	v_lshlrev_b32_e32 v252, 16, v246
	v_and_b32_e32 v253, 0xffff0000, v246
	v_lshlrev_b32_e32 v254, 16, v247
	v_and_b32_e32 v255, 0xffff0000, v247
	v_pk_add_f32 v[252:253], v[0:1], v[252:253]
	v_pk_add_f32 v[254:255], v[2:3], v[254:255]
	v_fmac_f32_e32 v175, v252, v252
	v_fmac_f32_e32 v175, v253, v253
	v_fmac_f32_e32 v175, v254, v254
	v_fmac_f32_e32 v175, v255, v255
	v_cvt_pk_bf16_f32 v190, v252, v253
	v_cvt_pk_bf16_f32 v191, v254, v255
	global_store_dwordx2 v142, v[190:191], s[96:97] offset:288
	s_branch .LresF_red
.LresF_xin:
	v_lshlrev_b32_e32 v141, 12, v138
	v_lshl_add_u32 v141, v140, 2, v141
	global_load_dwordx4 v[192:195], v141, s[4:5]
	global_load_dwordx4 v[196:199], v141, s[4:5] offset:64
	global_load_dwordx4 v[200:203], v141, s[4:5] offset:512
	global_load_dwordx4 v[204:207], v141, s[4:5] offset:576
	v_add_u32_e32 v141, 0x10000, v141
	global_load_dwordx4 v[208:211], v141, s[4:5]
	global_load_dwordx4 v[212:215], v141, s[4:5] offset:64
	global_load_dwordx4 v[216:219], v141, s[4:5] offset:512
	global_load_dwordx4 v[220:223], v141, s[4:5] offset:576
	v_add_u32_e32 v141, 0x10000, v141
	global_load_dwordx4 v[144:147], v141, s[4:5]
	global_load_dwordx4 v[148:151], v141, s[4:5] offset:64
	global_load_dwordx4 v[152:155], v141, s[4:5] offset:512
	global_load_dwordx4 v[156:159], v141, s[4:5] offset:576
	v_add_u32_e32 v141, 0x10000, v141
	global_load_dwordx4 v[160:163], v141, s[4:5]
	global_load_dwordx4 v[164:167], v141, s[4:5] offset:64
	global_load_dwordx4 v[240:243], v141, s[4:5] offset:512
	global_load_dwordx4 v[244:247], v141, s[4:5] offset:576
	v_add_u32_e32 v141, 0x50000, v141
	s_waitcnt vmcnt(15)
	v_pk_add_f32 v[252:253], v[124:125], v[192:193]
	v_pk_add_f32 v[254:255], v[126:127], v[194:195]
	v_mul_f32_e32 v128, v252, v252
	v_fmac_f32_e32 v128, v253, v253
	v_fmac_f32_e32 v128, v254, v254
	v_fmac_f32_e32 v128, v255, v255
	v_cvt_pk_bf16_f32 v190, v252, v253
	v_cvt_pk_bf16_f32 v191, v254, v255
	global_store_dwordx2 v142, v[190:191], s[96:97]
	s_waitcnt vmcnt(15)
	v_pk_add_f32 v[252:253], v[120:121], v[196:197]
	v_pk_add_f32 v[254:255], v[122:123], v[198:199]
	v_fmac_f32_e32 v128, v252, v252
	v_fmac_f32_e32 v128, v253, v253
	v_fmac_f32_e32 v128, v254, v254
	v_fmac_f32_e32 v128, v255, v255
	v_cvt_pk_bf16_f32 v190, v252, v253
	v_cvt_pk_bf16_f32 v191, v254, v255
	global_store_dwordx2 v142, v[190:191], s[96:97] offset:32
	s_waitcnt vmcnt(15)
	v_pk_add_f32 v[252:253], v[108:109], v[200:201]
	v_pk_add_f32 v[254:255], v[110:111], v[202:203]
	v_fmac_f32_e32 v128, v252, v252
	v_fmac_f32_e32 v128, v253, v253
	v_fmac_f32_e32 v128, v254, v254
	v_fmac_f32_e32 v128, v255, v255
	v_cvt_pk_bf16_f32 v190, v252, v253
	v_cvt_pk_bf16_f32 v191, v254, v255
	global_store_dwordx2 v142, v[190:191], s[96:97] offset:256
	s_waitcnt vmcnt(15)
	v_pk_add_f32 v[252:253], v[100:101], v[204:205]
	v_pk_add_f32 v[254:255], v[102:103], v[206:207]
	v_fmac_f32_e32 v128, v252, v252
	v_fmac_f32_e32 v128, v253, v253
	v_fmac_f32_e32 v128, v254, v254
	v_fmac_f32_e32 v128, v255, v255
	v_cvt_pk_bf16_f32 v190, v252, v253
	v_cvt_pk_bf16_f32 v191, v254, v255
	global_store_dwordx2 v142, v[190:191], s[96:97] offset:288
	v_add_u32_e32 v142, 0x8000, v142
	s_waitcnt vmcnt(15)
	v_pk_add_f32 v[252:253], v[116:117], v[208:209]
	v_pk_add_f32 v[254:255], v[118:119], v[210:211]
	v_mul_f32_e32 v129, v252, v252
	v_fmac_f32_e32 v129, v253, v253
	v_fmac_f32_e32 v129, v254, v254
	v_fmac_f32_e32 v129, v255, v255
	v_cvt_pk_bf16_f32 v190, v252, v253
	v_cvt_pk_bf16_f32 v191, v254, v255
	global_store_dwordx2 v142, v[190:191], s[96:97]
	s_waitcnt vmcnt(15)
	v_pk_add_f32 v[252:253], v[112:113], v[212:213]
	v_pk_add_f32 v[254:255], v[114:115], v[214:215]
	v_fmac_f32_e32 v129, v252, v252
	v_fmac_f32_e32 v129, v253, v253
	v_fmac_f32_e32 v129, v254, v254
	v_fmac_f32_e32 v129, v255, v255
	v_cvt_pk_bf16_f32 v190, v252, v253
	v_cvt_pk_bf16_f32 v191, v254, v255
	global_store_dwordx2 v142, v[190:191], s[96:97] offset:32
	s_waitcnt vmcnt(15)
	v_pk_add_f32 v[252:253], v[92:93], v[216:217]
	v_pk_add_f32 v[254:255], v[94:95], v[218:219]
	v_fmac_f32_e32 v129, v252, v252
	v_fmac_f32_e32 v129, v253, v253
	v_fmac_f32_e32 v129, v254, v254
	v_fmac_f32_e32 v129, v255, v255
	v_cvt_pk_bf16_f32 v190, v252, v253
	v_cvt_pk_bf16_f32 v191, v254, v255
	global_store_dwordx2 v142, v[190:191], s[96:97] offset:256
	s_waitcnt vmcnt(15)
	v_pk_add_f32 v[252:253], v[84:85], v[220:221]
	v_pk_add_f32 v[254:255], v[86:87], v[222:223]
	v_fmac_f32_e32 v129, v252, v252
	v_fmac_f32_e32 v129, v253, v253
	v_fmac_f32_e32 v129, v254, v254
	v_fmac_f32_e32 v129, v255, v255
	v_cvt_pk_bf16_f32 v190, v252, v253
	v_cvt_pk_bf16_f32 v191, v254, v255
	global_store_dwordx2 v142, v[190:191], s[96:97] offset:288
	v_add_u32_e32 v142, 0x8000, v142
	s_waitcnt vmcnt(15)
	v_pk_add_f32 v[252:253], v[104:105], v[144:145]
	v_pk_add_f32 v[254:255], v[106:107], v[146:147]
	v_mul_f32_e32 v130, v252, v252
	v_fmac_f32_e32 v130, v253, v253
	v_fmac_f32_e32 v130, v254, v254
	v_fmac_f32_e32 v130, v255, v255
	v_cvt_pk_bf16_f32 v190, v252, v253
	v_cvt_pk_bf16_f32 v191, v254, v255
	global_store_dwordx2 v142, v[190:191], s[96:97]
	s_waitcnt vmcnt(15)
	v_pk_add_f32 v[252:253], v[96:97], v[148:149]
	v_pk_add_f32 v[254:255], v[98:99], v[150:151]
	v_fmac_f32_e32 v130, v252, v252
	v_fmac_f32_e32 v130, v253, v253
	v_fmac_f32_e32 v130, v254, v254
	v_fmac_f32_e32 v130, v255, v255
	v_cvt_pk_bf16_f32 v190, v252, v253
	v_cvt_pk_bf16_f32 v191, v254, v255
	global_store_dwordx2 v142, v[190:191], s[96:97] offset:32
	s_waitcnt vmcnt(15)
	v_pk_add_f32 v[252:253], v[76:77], v[152:153]
	v_pk_add_f32 v[254:255], v[78:79], v[154:155]
	v_fmac_f32_e32 v130, v252, v252
	v_fmac_f32_e32 v130, v253, v253
	v_fmac_f32_e32 v130, v254, v254
	v_fmac_f32_e32 v130, v255, v255
	v_cvt_pk_bf16_f32 v190, v252, v253
	v_cvt_pk_bf16_f32 v191, v254, v255
	global_store_dwordx2 v142, v[190:191], s[96:97] offset:256
	s_waitcnt vmcnt(15)
	v_pk_add_f32 v[252:253], v[72:73], v[156:157]
	v_pk_add_f32 v[254:255], v[74:75], v[158:159]
	v_fmac_f32_e32 v130, v252, v252
	v_fmac_f32_e32 v130, v253, v253
	v_fmac_f32_e32 v130, v254, v254
	v_fmac_f32_e32 v130, v255, v255
	v_cvt_pk_bf16_f32 v190, v252, v253
	v_cvt_pk_bf16_f32 v191, v254, v255
	global_store_dwordx2 v142, v[190:191], s[96:97] offset:288
	v_add_u32_e32 v142, 0x8000, v142
	s_waitcnt vmcnt(15)
	v_pk_add_f32 v[252:253], v[88:89], v[160:161]
	v_pk_add_f32 v[254:255], v[90:91], v[162:163]
	v_mul_f32_e32 v131, v252, v252
	v_fmac_f32_e32 v131, v253, v253
	v_fmac_f32_e32 v131, v254, v254
	v_fmac_f32_e32 v131, v255, v255
	v_cvt_pk_bf16_f32 v190, v252, v253
	v_cvt_pk_bf16_f32 v191, v254, v255
	global_store_dwordx2 v142, v[190:191], s[96:97]
	s_waitcnt vmcnt(15)
	v_pk_add_f32 v[252:253], v[80:81], v[164:165]
	v_pk_add_f32 v[254:255], v[82:83], v[166:167]
	v_fmac_f32_e32 v131, v252, v252
	v_fmac_f32_e32 v131, v253, v253
	v_fmac_f32_e32 v131, v254, v254
	v_fmac_f32_e32 v131, v255, v255
	v_cvt_pk_bf16_f32 v190, v252, v253
	v_cvt_pk_bf16_f32 v191, v254, v255
	global_store_dwordx2 v142, v[190:191], s[96:97] offset:32
	s_waitcnt vmcnt(15)
	v_pk_add_f32 v[252:253], v[68:69], v[240:241]
	v_pk_add_f32 v[254:255], v[70:71], v[242:243]
	v_fmac_f32_e32 v131, v252, v252
	v_fmac_f32_e32 v131, v253, v253
	v_fmac_f32_e32 v131, v254, v254
	v_fmac_f32_e32 v131, v255, v255
	v_cvt_pk_bf16_f32 v190, v252, v253
	v_cvt_pk_bf16_f32 v191, v254, v255
	global_store_dwordx2 v142, v[190:191], s[96:97] offset:256
	s_waitcnt vmcnt(15)
	v_pk_add_f32 v[252:253], v[64:65], v[244:245]
	v_pk_add_f32 v[254:255], v[66:67], v[246:247]
	v_fmac_f32_e32 v131, v252, v252
	v_fmac_f32_e32 v131, v253, v253
	v_fmac_f32_e32 v131, v254, v254
	v_fmac_f32_e32 v131, v255, v255
	v_cvt_pk_bf16_f32 v190, v252, v253
	v_cvt_pk_bf16_f32 v191, v254, v255
	global_store_dwordx2 v142, v[190:191], s[96:97] offset:288
	v_add_u32_e32 v142, 0x28000, v142
	global_load_dwordx4 v[192:195], v141, s[4:5]
	global_load_dwordx4 v[196:199], v141, s[4:5] offset:64
	global_load_dwordx4 v[200:203], v141, s[4:5] offset:512
	global_load_dwordx4 v[204:207], v141, s[4:5] offset:576
	v_add_u32_e32 v141, 0x10000, v141
	global_load_dwordx4 v[208:211], v141, s[4:5]
	global_load_dwordx4 v[212:215], v141, s[4:5] offset:64
	global_load_dwordx4 v[216:219], v141, s[4:5] offset:512
	global_load_dwordx4 v[220:223], v141, s[4:5] offset:576
	v_add_u32_e32 v141, 0x10000, v141
	global_load_dwordx4 v[144:147], v141, s[4:5]
	global_load_dwordx4 v[148:151], v141, s[4:5] offset:64
	global_load_dwordx4 v[152:155], v141, s[4:5] offset:512
	global_load_dwordx4 v[156:159], v141, s[4:5] offset:576
	v_add_u32_e32 v141, 0x10000, v141
	global_load_dwordx4 v[160:163], v141, s[4:5]
	global_load_dwordx4 v[164:167], v141, s[4:5] offset:64
	global_load_dwordx4 v[240:243], v141, s[4:5] offset:512
	global_load_dwordx4 v[244:247], v141, s[4:5] offset:576
	s_waitcnt vmcnt(15)
	v_pk_add_f32 v[252:253], v[60:61], v[192:193]
	v_pk_add_f32 v[254:255], v[62:63], v[194:195]
	v_mul_f32_e32 v172, v252, v252
	v_fmac_f32_e32 v172, v253, v253
	v_fmac_f32_e32 v172, v254, v254
	v_fmac_f32_e32 v172, v255, v255
	v_cvt_pk_bf16_f32 v190, v252, v253
	v_cvt_pk_bf16_f32 v191, v254, v255
	global_store_dwordx2 v142, v[190:191], s[96:97]
	s_waitcnt vmcnt(15)
	v_pk_add_f32 v[252:253], v[56:57], v[196:197]
	v_pk_add_f32 v[254:255], v[58:59], v[198:199]
	v_fmac_f32_e32 v172, v252, v252
	v_fmac_f32_e32 v172, v253, v253
	v_fmac_f32_e32 v172, v254, v254
	v_fmac_f32_e32 v172, v255, v255
	v_cvt_pk_bf16_f32 v190, v252, v253
	v_cvt_pk_bf16_f32 v191, v254, v255
	global_store_dwordx2 v142, v[190:191], s[96:97] offset:32
	s_waitcnt vmcnt(15)
	v_pk_add_f32 v[252:253], v[44:45], v[200:201]
	v_pk_add_f32 v[254:255], v[46:47], v[202:203]
	v_fmac_f32_e32 v172, v252, v252
	v_fmac_f32_e32 v172, v253, v253
	v_fmac_f32_e32 v172, v254, v254
	v_fmac_f32_e32 v172, v255, v255
	v_cvt_pk_bf16_f32 v190, v252, v253
	v_cvt_pk_bf16_f32 v191, v254, v255
	global_store_dwordx2 v142, v[190:191], s[96:97] offset:256
	s_waitcnt vmcnt(15)
	v_pk_add_f32 v[252:253], v[36:37], v[204:205]
	v_pk_add_f32 v[254:255], v[38:39], v[206:207]
	v_fmac_f32_e32 v172, v252, v252
	v_fmac_f32_e32 v172, v253, v253
	v_fmac_f32_e32 v172, v254, v254
	v_fmac_f32_e32 v172, v255, v255
	v_cvt_pk_bf16_f32 v190, v252, v253
	v_cvt_pk_bf16_f32 v191, v254, v255
	global_store_dwordx2 v142, v[190:191], s[96:97] offset:288
	v_add_u32_e32 v142, 0x8000, v142
	s_waitcnt vmcnt(15)
	v_pk_add_f32 v[252:253], v[52:53], v[208:209]
	v_pk_add_f32 v[254:255], v[54:55], v[210:211]
	v_mul_f32_e32 v173, v252, v252
	v_fmac_f32_e32 v173, v253, v253
	v_fmac_f32_e32 v173, v254, v254
	v_fmac_f32_e32 v173, v255, v255
	v_cvt_pk_bf16_f32 v190, v252, v253
	v_cvt_pk_bf16_f32 v191, v254, v255
	global_store_dwordx2 v142, v[190:191], s[96:97]
	s_waitcnt vmcnt(15)
	v_pk_add_f32 v[252:253], v[48:49], v[212:213]
	v_pk_add_f32 v[254:255], v[50:51], v[214:215]
	v_fmac_f32_e32 v173, v252, v252
	v_fmac_f32_e32 v173, v253, v253
	v_fmac_f32_e32 v173, v254, v254
	v_fmac_f32_e32 v173, v255, v255
	v_cvt_pk_bf16_f32 v190, v252, v253
	v_cvt_pk_bf16_f32 v191, v254, v255
	global_store_dwordx2 v142, v[190:191], s[96:97] offset:32
	s_waitcnt vmcnt(15)
	v_pk_add_f32 v[252:253], v[28:29], v[216:217]
	v_pk_add_f32 v[254:255], v[30:31], v[218:219]
	v_fmac_f32_e32 v173, v252, v252
	v_fmac_f32_e32 v173, v253, v253
	v_fmac_f32_e32 v173, v254, v254
	v_fmac_f32_e32 v173, v255, v255
	v_cvt_pk_bf16_f32 v190, v252, v253
	v_cvt_pk_bf16_f32 v191, v254, v255
	global_store_dwordx2 v142, v[190:191], s[96:97] offset:256
	s_waitcnt vmcnt(15)
	v_pk_add_f32 v[252:253], v[20:21], v[220:221]
	v_pk_add_f32 v[254:255], v[22:23], v[222:223]
	v_fmac_f32_e32 v173, v252, v252
	v_fmac_f32_e32 v173, v253, v253
	v_fmac_f32_e32 v173, v254, v254
	v_fmac_f32_e32 v173, v255, v255
	v_cvt_pk_bf16_f32 v190, v252, v253
	v_cvt_pk_bf16_f32 v191, v254, v255
	global_store_dwordx2 v142, v[190:191], s[96:97] offset:288
	v_add_u32_e32 v142, 0x8000, v142
	s_waitcnt vmcnt(15)
	v_pk_add_f32 v[252:253], v[40:41], v[144:145]
	v_pk_add_f32 v[254:255], v[42:43], v[146:147]
	v_mul_f32_e32 v174, v252, v252
	v_fmac_f32_e32 v174, v253, v253
	v_fmac_f32_e32 v174, v254, v254
	v_fmac_f32_e32 v174, v255, v255
	v_cvt_pk_bf16_f32 v190, v252, v253
	v_cvt_pk_bf16_f32 v191, v254, v255
	global_store_dwordx2 v142, v[190:191], s[96:97]
	s_waitcnt vmcnt(15)
	v_pk_add_f32 v[252:253], v[32:33], v[148:149]
	v_pk_add_f32 v[254:255], v[34:35], v[150:151]
	v_fmac_f32_e32 v174, v252, v252
	v_fmac_f32_e32 v174, v253, v253
	v_fmac_f32_e32 v174, v254, v254
	v_fmac_f32_e32 v174, v255, v255
	v_cvt_pk_bf16_f32 v190, v252, v253
	v_cvt_pk_bf16_f32 v191, v254, v255
	global_store_dwordx2 v142, v[190:191], s[96:97] offset:32
	s_waitcnt vmcnt(15)
	v_pk_add_f32 v[252:253], v[12:13], v[152:153]
	v_pk_add_f32 v[254:255], v[14:15], v[154:155]
	v_fmac_f32_e32 v174, v252, v252
	v_fmac_f32_e32 v174, v253, v253
	v_fmac_f32_e32 v174, v254, v254
	v_fmac_f32_e32 v174, v255, v255
	v_cvt_pk_bf16_f32 v190, v252, v253
	v_cvt_pk_bf16_f32 v191, v254, v255
	global_store_dwordx2 v142, v[190:191], s[96:97] offset:256
	s_waitcnt vmcnt(15)
	v_pk_add_f32 v[252:253], v[8:9], v[156:157]
	v_pk_add_f32 v[254:255], v[10:11], v[158:159]
	v_fmac_f32_e32 v174, v252, v252
	v_fmac_f32_e32 v174, v253, v253
	v_fmac_f32_e32 v174, v254, v254
	v_fmac_f32_e32 v174, v255, v255
	v_cvt_pk_bf16_f32 v190, v252, v253
	v_cvt_pk_bf16_f32 v191, v254, v255
	global_store_dwordx2 v142, v[190:191], s[96:97] offset:288
	v_add_u32_e32 v142, 0x8000, v142
	s_waitcnt vmcnt(15)
	v_pk_add_f32 v[252:253], v[24:25], v[160:161]
	v_pk_add_f32 v[254:255], v[26:27], v[162:163]
	v_mul_f32_e32 v175, v252, v252
	v_fmac_f32_e32 v175, v253, v253
	v_fmac_f32_e32 v175, v254, v254
	v_fmac_f32_e32 v175, v255, v255
	v_cvt_pk_bf16_f32 v190, v252, v253
	v_cvt_pk_bf16_f32 v191, v254, v255
	global_store_dwordx2 v142, v[190:191], s[96:97]
	s_waitcnt vmcnt(15)
	v_pk_add_f32 v[252:253], v[16:17], v[164:165]
	v_pk_add_f32 v[254:255], v[18:19], v[166:167]
	v_fmac_f32_e32 v175, v252, v252
	v_fmac_f32_e32 v175, v253, v253
	v_fmac_f32_e32 v175, v254, v254
	v_fmac_f32_e32 v175, v255, v255
	v_cvt_pk_bf16_f32 v190, v252, v253
	v_cvt_pk_bf16_f32 v191, v254, v255
	global_store_dwordx2 v142, v[190:191], s[96:97] offset:32
	s_waitcnt vmcnt(15)
	v_pk_add_f32 v[252:253], v[4:5], v[240:241]
	v_pk_add_f32 v[254:255], v[6:7], v[242:243]
	v_fmac_f32_e32 v175, v252, v252
	v_fmac_f32_e32 v175, v253, v253
	v_fmac_f32_e32 v175, v254, v254
	v_fmac_f32_e32 v175, v255, v255
	v_cvt_pk_bf16_f32 v190, v252, v253
	v_cvt_pk_bf16_f32 v191, v254, v255
	global_store_dwordx2 v142, v[190:191], s[96:97] offset:256
	s_waitcnt vmcnt(15)
	v_pk_add_f32 v[252:253], v[0:1], v[244:245]
	v_pk_add_f32 v[254:255], v[2:3], v[246:247]
	v_fmac_f32_e32 v175, v252, v252
	v_fmac_f32_e32 v175, v253, v253
	v_fmac_f32_e32 v175, v254, v254
	v_fmac_f32_e32 v175, v255, v255
	v_cvt_pk_bf16_f32 v190, v252, v253
	v_cvt_pk_bf16_f32 v191, v254, v255
	global_store_dwordx2 v142, v[190:191], s[96:97] offset:288
.LresF_red:
	ds_bpermute_b32 v192, v238, v128
	ds_bpermute_b32 v193, v238, v129
	ds_bpermute_b32 v194, v238, v130
	ds_bpermute_b32 v195, v238, v131
	ds_bpermute_b32 v196, v238, v172
	ds_bpermute_b32 v197, v238, v173
	ds_bpermute_b32 v198, v238, v174
	ds_bpermute_b32 v199, v238, v175
	s_waitcnt lgkmcnt(0)
	v_add_f32_e32 v128, v128, v192
	v_add_f32_e32 v129, v129, v193
	v_add_f32_e32 v130, v130, v194
	v_add_f32_e32 v131, v131, v195
	v_add_f32_e32 v172, v172, v196
	v_add_f32_e32 v173, v173, v197
	v_add_f32_e32 v174, v174, v198
	v_add_f32_e32 v175, v175, v199
	ds_bpermute_b32 v192, v239, v128
	ds_bpermute_b32 v193, v239, v129
	ds_bpermute_b32 v194, v239, v130
	ds_bpermute_b32 v195, v239, v131
	ds_bpermute_b32 v196, v239, v172
	ds_bpermute_b32 v197, v239, v173
	ds_bpermute_b32 v198, v239, v174
	ds_bpermute_b32 v199, v239, v175
	s_waitcnt lgkmcnt(0)
	v_add_f32_e32 v128, v128, v192
	v_add_f32_e32 v129, v129, v193
	v_add_f32_e32 v130, v130, v194
	v_add_f32_e32 v131, v131, v195
	v_add_f32_e32 v172, v172, v196
	v_add_f32_e32 v173, v173, v197
	v_add_f32_e32 v174, v174, v198
	v_add_f32_e32 v175, v175, v199
	v_cmp_eq_u32_e32 vcc, 0, v169
	s_and_saveexec_b64 s[40:41], vcc
	global_atomic_add_f32 v143, v128, s[10:11]
	global_atomic_add_f32 v143, v129, s[10:11] offset:64
	global_atomic_add_f32 v143, v130, s[10:11] offset:128
	global_atomic_add_f32 v143, v131, s[10:11] offset:192
	global_atomic_add_f32 v143, v172, s[10:11] offset:512
	global_atomic_add_f32 v143, v173, s[10:11] offset:576
	global_atomic_add_f32 v143, v174, s[10:11] offset:640
	global_atomic_add_f32 v143, v175, s[10:11] offset:704
	s_or_b64 exec, exec, s[40:41]
.LresF_done:
	s_mov_b64 s[22:23], 0
.LBB0_1474:
	s_and_b64 vcc, exec, s[22:23]
	s_cbranch_vccz .LBB0_1311
	s_add_i32 s86, s47, -1
	s_lshl_b64 s[22:23], s[86:87], 21
	s_add_u32 s22, s29, s22
	v_add_u32_e32 v128, 0xffff8000, v138
	s_addc_u32 s23, s50, s23
	s_waitcnt lgkmcnt(0)
	v_ashrrev_i32_e32 v129, 31, v128
	v_lshl_add_u64 v[130:131], v[140:141], 2, s[22:23]
	v_lshlrev_b64 v[128:129], 12, v[128:129]
	v_lshl_add_u64 v[128:129], v[130:131], 0, v[128:129]
	global_store_dwordx4 v[128:129], v[124:127], off
	global_store_dwordx4 v[128:129], v[120:123], off offset:64
	global_store_dwordx4 v[128:129], v[108:111], off offset:512
	global_store_dwordx4 v[128:129], v[100:103], off offset:576
	s_nop 1
	v_add_u32_e32 v100, 0xffff8010, v138
	v_ashrrev_i32_e32 v101, 31, v100
	v_lshlrev_b64 v[100:101], 12, v[100:101]
	v_lshl_add_u64 v[100:101], v[130:131], 0, v[100:101]
	global_store_dwordx4 v[100:101], v[116:119], off
	global_store_dwordx4 v[100:101], v[112:115], off offset:64
	global_store_dwordx4 v[100:101], v[92:95], off offset:512
	global_store_dwordx4 v[100:101], v[84:87], off offset:576
	s_nop 1
	v_add_u32_e32 v84, 0xffff8020, v138
	v_ashrrev_i32_e32 v85, 31, v84
	v_lshlrev_b64 v[84:85], 12, v[84:85]
	v_lshl_add_u64 v[84:85], v[130:131], 0, v[84:85]
	global_store_dwordx4 v[84:85], v[104:107], off
	global_store_dwordx4 v[84:85], v[96:99], off offset:64
	global_store_dwordx4 v[84:85], v[76:79], off offset:512
	global_store_dwordx4 v[84:85], v[72:75], off offset:576
	s_nop 1
	v_add_u32_e32 v72, 0xffff8030, v138
	v_ashrrev_i32_e32 v73, 31, v72
	v_lshlrev_b64 v[72:73], 12, v[72:73]
	v_lshl_add_u64 v[72:73], v[130:131], 0, v[72:73]
	global_store_dwordx4 v[72:73], v[88:91], off
	global_store_dwordx4 v[72:73], v[80:83], off offset:64
	global_store_dwordx4 v[72:73], v[68:71], off offset:512
	global_store_dwordx4 v[72:73], v[64:67], off offset:576
	s_nop 1
	v_add_u32_e32 v64, 0xffff8080, v138
	v_ashrrev_i32_e32 v65, 31, v64
	v_lshlrev_b64 v[64:65], 12, v[64:65]
	v_lshl_add_u64 v[64:65], v[130:131], 0, v[64:65]
	global_store_dwordx4 v[64:65], v[60:63], off
	global_store_dwordx4 v[64:65], v[56:59], off offset:64
	global_store_dwordx4 v[64:65], v[44:47], off offset:512
	global_store_dwordx4 v[64:65], v[36:39], off offset:576
	s_nop 1
	v_add_u32_e32 v36, 0xffff8090, v138
	v_ashrrev_i32_e32 v37, 31, v36
	v_lshlrev_b64 v[36:37], 12, v[36:37]
	v_lshl_add_u64 v[36:37], v[130:131], 0, v[36:37]
	global_store_dwordx4 v[36:37], v[52:55], off
	global_store_dwordx4 v[36:37], v[48:51], off offset:64
	global_store_dwordx4 v[36:37], v[28:31], off offset:512
	global_store_dwordx4 v[36:37], v[20:23], off offset:576
	s_nop 1
	v_add_u32_e32 v20, 0xffff80a0, v138
	v_ashrrev_i32_e32 v21, 31, v20
	v_lshlrev_b64 v[20:21], 12, v[20:21]
	v_lshl_add_u64 v[20:21], v[130:131], 0, v[20:21]
	global_store_dwordx4 v[20:21], v[40:43], off
	global_store_dwordx4 v[20:21], v[32:35], off offset:64
	global_store_dwordx4 v[20:21], v[12:15], off offset:512
	global_store_dwordx4 v[20:21], v[8:11], off offset:576
	s_nop 1
	v_add_u32_e32 v8, 0xffff80b0, v138
	v_ashrrev_i32_e32 v9, 31, v8
	v_lshlrev_b64 v[8:9], 12, v[8:9]
	v_lshl_add_u64 v[8:9], v[130:131], 0, v[8:9]
	global_store_dwordx4 v[8:9], v[24:27], off
	global_store_dwordx4 v[8:9], v[16:19], off offset:64
	global_store_dwordx4 v[8:9], v[4:7], off offset:512
	global_store_dwordx4 v[8:9], v[0:3], off offset:576
	s_branch .LBB0_1311
.LBB0_1479:
	s_waitcnt vmcnt(0)
	s_cmpk_gt_u32 s46, 0xff
	s_cbranch_scc1 .LBB0_1481
	s_barrier

.LBB0_1787:
	s_add_i32 s60, s16, 2
	s_add_u32 s14, s12, 0x100
	s_addc_u32 s15, s13, 0
	s_add_i32 s61, 0, 0x10000
	v_add_u32_e32 v140, s61, v162
	s_waitcnt lgkmcnt(0)
	ds_read_b128 v[128:131], v140
	ds_read_b128 v[132:135], v140 offset:1024
	ds_read_b128 v[136:139], v140 offset:2048
	ds_read_b128 v[140:143], v140 offset:3072
	s_cmp_eq_u32 s57, s16
	s_cselect_b32 s16, s56, s58
	s_cselect_b32 s19, s43, s15
	s_cselect_b32 s18, s44, s14
	s_cselect_b32 s17, s45, s59
	v_lshl_add_u64 v[158:159], s[12:13], 0, v[146:147]
	s_add_i32 m0, s35, 0xc000
	ds_read_b128 v[150:153], v163
	ds_read_b128 v[154:157], v163 offset:1024
	ds_read_b128 v[164:167], v163 offset:2048
	ds_read_b128 v[168:171], v163 offset:3072
	ds_read_b128 v[172:175], v163 offset:4096
	ds_read_b128 v[190:193], v163 offset:5120
	ds_read_b128 v[194:197], v163 offset:6144
	ds_read_b128 v[198:201], v163 offset:7168
	global_load_lds_dwordx4 v[158:159], off
	v_lshl_add_u64 v[158:159], s[12:13], 0, v[148:149]
	s_add_i32 m0, s35, 0xe000
	s_nop 0
	global_load_lds_dwordx4 v[158:159], off
	s_waitcnt lgkmcnt(8)
	s_barrier
	s_waitcnt lgkmcnt(0)
	s_setprio 1
	s_waitcnt lgkmcnt(0)
	v_mfma_f32_16x16x32_bf16 v[124:127], v[128:131], v[150:153], v[124:127]
	v_mfma_f32_16x16x32_bf16 v[120:123], v[136:139], v[150:153], v[120:123]
	v_mfma_f32_16x16x32_bf16 v[116:119], v[128:131], v[164:167], v[116:119]
	v_mfma_f32_16x16x32_bf16 v[112:115], v[136:139], v[164:167], v[112:115]
	v_mfma_f32_16x16x32_bf16 v[104:107], v[128:131], v[172:175], v[104:107]
	v_mfma_f32_16x16x32_bf16 v[96:99], v[136:139], v[172:175], v[96:99]
	v_mfma_f32_16x16x32_bf16 v[88:91], v[128:131], v[194:197], v[88:91]
	v_mfma_f32_16x16x32_bf16 v[80:83], v[136:139], v[194:197], v[80:83]
	v_mfma_f32_16x16x32_bf16 v[124:127], v[132:135], v[154:157], v[124:127]
	v_mfma_f32_16x16x32_bf16 v[120:123], v[140:143], v[154:157], v[120:123]
	v_mfma_f32_16x16x32_bf16 v[116:119], v[132:135], v[168:171], v[116:119]
	v_mfma_f32_16x16x32_bf16 v[112:115], v[140:143], v[168:171], v[112:115]
	v_mfma_f32_16x16x32_bf16 v[104:107], v[132:135], v[190:193], v[104:107]
	v_mfma_f32_16x16x32_bf16 v[96:99], v[140:143], v[190:193], v[96:99]
	v_mfma_f32_16x16x32_bf16 v[88:91], v[132:135], v[198:201], v[88:91]
	v_mfma_f32_16x16x32_bf16 v[80:83], v[140:143], v[198:201], v[80:83]
	s_setprio 0
	s_barrier
	s_add_i32 s62, 0, 0x14000
	v_add_u32_e32 v158, s62, v162
	s_add_i32 s12, s61, s34
	ds_read_b128 v[202:205], v158
	ds_read_b128 v[206:209], v158 offset:1024
	ds_read_b128 v[210:213], v158 offset:2048
	ds_read_b128 v[214:217], v158 offset:3072
	v_lshl_add_u64 v[158:159], s[16:17], 0, v[176:177]
	s_mov_b32 m0, s12
	v_lshl_add_u64 v[218:219], s[16:17], 0, v[144:145]
	global_load_lds_dwordx4 v[158:159], off
	s_add_i32 m0, s12, 0x2000
	s_nop 0
	global_load_lds_dwordx4 v[218:219], off
	s_barrier
	s_waitcnt lgkmcnt(0)
	s_setprio 1
	s_waitcnt lgkmcnt(0)
	v_mfma_f32_16x16x32_bf16 v[108:111], v[202:205], v[150:153], v[108:111]
	v_mfma_f32_16x16x32_bf16 v[100:103], v[210:213], v[150:153], v[100:103]
	v_mfma_f32_16x16x32_bf16 v[92:95], v[202:205], v[164:167], v[92:95]
	v_mfma_f32_16x16x32_bf16 v[84:87], v[210:213], v[164:167], v[84:87]
	v_mfma_f32_16x16x32_bf16 v[76:79], v[202:205], v[172:175], v[76:79]
	v_mfma_f32_16x16x32_bf16 v[72:75], v[210:213], v[172:175], v[72:75]
	v_mfma_f32_16x16x32_bf16 v[68:71], v[202:205], v[194:197], v[68:71]
	v_mfma_f32_16x16x32_bf16 v[64:67], v[210:213], v[194:197], v[64:67]
	v_mfma_f32_16x16x32_bf16 v[108:111], v[206:209], v[154:157], v[108:111]
	v_mfma_f32_16x16x32_bf16 v[100:103], v[214:217], v[154:157], v[100:103]
	v_mfma_f32_16x16x32_bf16 v[92:95], v[206:209], v[168:171], v[92:95]
	v_mfma_f32_16x16x32_bf16 v[84:87], v[214:217], v[168:171], v[84:87]
	v_mfma_f32_16x16x32_bf16 v[76:79], v[206:209], v[190:193], v[76:79]
	v_mfma_f32_16x16x32_bf16 v[72:75], v[214:217], v[190:193], v[72:75]
	v_mfma_f32_16x16x32_bf16 v[68:71], v[206:209], v[198:201], v[68:71]
	v_mfma_f32_16x16x32_bf16 v[64:67], v[214:217], v[198:201], v[64:67]
	s_setprio 0
	s_mov_b32 m0, s35
	v_lshl_add_u64 v[220:221], s[18:19], 0, v[176:177]
	s_barrier
	ds_read_b128 v[150:153], v163 offset:16384
	ds_read_b128 v[154:157], v163 offset:17408
	ds_read_b128 v[164:167], v163 offset:18432
	ds_read_b128 v[168:171], v163 offset:19456
	ds_read_b128 v[172:175], v163 offset:20480
	ds_read_b128 v[190:193], v163 offset:21504
	ds_read_b128 v[194:197], v163 offset:22528
	ds_read_b128 v[198:201], v163 offset:23552
	global_load_lds_dwordx4 v[220:221], off
	v_lshl_add_u64 v[222:223], s[18:19], 0, v[144:145]
	s_mov_b32 m0, s36
	s_nop 0
	global_load_lds_dwordx4 v[222:223], off
	s_barrier
	s_waitcnt lgkmcnt(0)
	s_setprio 1
	s_waitcnt lgkmcnt(0)
	v_mfma_f32_16x16x32_bf16 v[60:63], v[128:131], v[150:153], v[60:63]
	v_mfma_f32_16x16x32_bf16 v[56:59], v[136:139], v[150:153], v[56:59]
	v_mfma_f32_16x16x32_bf16 v[52:55], v[128:131], v[164:167], v[52:55]
	v_mfma_f32_16x16x32_bf16 v[48:51], v[136:139], v[164:167], v[48:51]
	v_mfma_f32_16x16x32_bf16 v[40:43], v[128:131], v[172:175], v[40:43]
	v_mfma_f32_16x16x32_bf16 v[32:35], v[136:139], v[172:175], v[32:35]
	v_mfma_f32_16x16x32_bf16 v[24:27], v[128:131], v[194:197], v[24:27]
	v_mfma_f32_16x16x32_bf16 v[16:19], v[136:139], v[194:197], v[16:19]
	v_mfma_f32_16x16x32_bf16 v[60:63], v[132:135], v[154:157], v[60:63]
	v_mfma_f32_16x16x32_bf16 v[56:59], v[140:143], v[154:157], v[56:59]
	v_mfma_f32_16x16x32_bf16 v[52:55], v[132:135], v[168:171], v[52:55]
	v_mfma_f32_16x16x32_bf16 v[48:51], v[140:143], v[168:171], v[48:51]
	v_mfma_f32_16x16x32_bf16 v[40:43], v[132:135], v[190:193], v[40:43]
	v_mfma_f32_16x16x32_bf16 v[32:35], v[140:143], v[190:193], v[32:35]
	v_mfma_f32_16x16x32_bf16 v[24:27], v[132:135], v[198:201], v[24:27]
	v_mfma_f32_16x16x32_bf16 v[16:19], v[140:143], v[198:201], v[16:19]
	s_setprio 0
	s_barrier
	s_add_u32 s12, s16, 0xb0000
	s_addc_u32 s13, s17, 0
	s_add_i32 s61, s62, s34
	v_lshl_add_u64 v[128:129], s[12:13], 0, v[176:177]
	s_mov_b32 m0, s61
	s_nop 0
	global_load_lds_dwordx4 v[128:129], off
	v_lshl_add_u64 v[128:129], s[12:13], 0, v[144:145]
	s_add_i32 m0, s61, 0x2000
	s_nop 0
	global_load_lds_dwordx4 v[128:129], off
	s_waitcnt vmcnt(6)
	s_barrier
	s_setprio 1
	v_mfma_f32_16x16x32_bf16 v[44:47], v[202:205], v[150:153], v[44:47]
	v_mfma_f32_16x16x32_bf16 v[36:39], v[210:213], v[150:153], v[36:39]
	v_mfma_f32_16x16x32_bf16 v[28:31], v[202:205], v[164:167], v[28:31]
	v_mfma_f32_16x16x32_bf16 v[20:23], v[210:213], v[164:167], v[20:23]
	v_mfma_f32_16x16x32_bf16 v[12:15], v[202:205], v[172:175], v[12:15]
	v_mfma_f32_16x16x32_bf16 v[8:11], v[210:213], v[172:175], v[8:11]
	v_mfma_f32_16x16x32_bf16 v[4:7], v[202:205], v[194:197], v[4:7]
	v_mfma_f32_16x16x32_bf16 v[0:3], v[210:213], v[194:197], v[0:3]
	v_mfma_f32_16x16x32_bf16 v[44:47], v[206:209], v[154:157], v[44:47]
	v_mfma_f32_16x16x32_bf16 v[36:39], v[214:217], v[154:157], v[36:39]
	v_mfma_f32_16x16x32_bf16 v[28:31], v[206:209], v[168:171], v[28:31]
	v_mfma_f32_16x16x32_bf16 v[20:23], v[214:217], v[168:171], v[20:23]
	v_mfma_f32_16x16x32_bf16 v[12:15], v[206:209], v[190:193], v[12:15]
	v_mfma_f32_16x16x32_bf16 v[8:11], v[214:217], v[190:193], v[8:11]
	v_mfma_f32_16x16x32_bf16 v[4:7], v[206:209], v[198:201], v[4:7]
	v_mfma_f32_16x16x32_bf16 v[0:3], v[214:217], v[198:201], v[0:3]
	s_setprio 0
	s_add_i32 s61, 0, 0x18000
	v_add_u32_e32 v140, s61, v162
	s_barrier
	ds_read_b128 v[128:131], v140
	ds_read_b128 v[132:135], v140 offset:1024
	ds_read_b128 v[136:139], v140 offset:2048
	ds_read_b128 v[140:143], v140 offset:3072
	s_add_u32 s12, s18, 0xb0000
	s_addc_u32 s13, s19, 0
	s_mov_b32 m0, s37
	v_lshl_add_u64 v[202:203], s[12:13], 0, v[176:177]
	ds_read_b128 v[150:153], v163 offset:32768
	ds_read_b128 v[154:157], v163 offset:33792
	ds_read_b128 v[164:167], v163 offset:34816
	ds_read_b128 v[168:171], v163 offset:35840
	ds_read_b128 v[172:175], v163 offset:36864
	ds_read_b128 v[190:193], v163 offset:37888
	ds_read_b128 v[194:197], v163 offset:38912
	ds_read_b128 v[198:201], v163 offset:39936
	global_load_lds_dwordx4 v[202:203], off
	v_lshl_add_u64 v[202:203], s[12:13], 0, v[144:145]
	s_mov_b32 m0, s38
	s_nop 0
	global_load_lds_dwordx4 v[202:203], off
	s_waitcnt lgkmcnt(8)
	s_barrier
	s_waitcnt lgkmcnt(0)
	s_setprio 1
	s_waitcnt lgkmcnt(0)
	v_mfma_f32_16x16x32_bf16 v[124:127], v[128:131], v[150:153], v[124:127]
	v_mfma_f32_16x16x32_bf16 v[120:123], v[136:139], v[150:153], v[120:123]
	v_mfma_f32_16x16x32_bf16 v[116:119], v[128:131], v[164:167], v[116:119]
	v_mfma_f32_16x16x32_bf16 v[112:115], v[136:139], v[164:167], v[112:115]
	v_mfma_f32_16x16x32_bf16 v[104:107], v[128:131], v[172:175], v[104:107]
	v_mfma_f32_16x16x32_bf16 v[96:99], v[136:139], v[172:175], v[96:99]
	v_mfma_f32_16x16x32_bf16 v[88:91], v[128:131], v[194:197], v[88:91]
	v_mfma_f32_16x16x32_bf16 v[80:83], v[136:139], v[194:197], v[80:83]
	v_mfma_f32_16x16x32_bf16 v[124:127], v[132:135], v[154:157], v[124:127]
	v_mfma_f32_16x16x32_bf16 v[120:123], v[140:143], v[154:157], v[120:123]
	v_mfma_f32_16x16x32_bf16 v[116:119], v[132:135], v[168:171], v[116:119]
	v_mfma_f32_16x16x32_bf16 v[112:115], v[140:143], v[168:171], v[112:115]
	v_mfma_f32_16x16x32_bf16 v[104:107], v[132:135], v[190:193], v[104:107]
	v_mfma_f32_16x16x32_bf16 v[96:99], v[140:143], v[190:193], v[96:99]
	v_mfma_f32_16x16x32_bf16 v[88:91], v[132:135], v[198:201], v[88:91]
	v_mfma_f32_16x16x32_bf16 v[80:83], v[140:143], v[198:201], v[80:83]
	s_setprio 0
	s_barrier
	s_add_i32 s18, 0, 0x1c000
	s_add_i32 s12, s61, s34
	v_add_u32_e32 v214, s18, v162
	v_lshl_add_u64 v[158:159], v[158:159], 0, s[24:25]
	s_mov_b32 m0, s12
	ds_read_b128 v[202:205], v214
	ds_read_b128 v[206:209], v214 offset:1024
	ds_read_b128 v[210:213], v214 offset:2048
	ds_read_b128 v[214:217], v214 offset:3072
	global_load_lds_dwordx4 v[158:159], off
	v_lshl_add_u64 v[158:159], v[218:219], 0, s[24:25]
	s_add_i32 m0, s12, 0x2000
	s_nop 0
	global_load_lds_dwordx4 v[158:159], off
	s_barrier
	s_waitcnt lgkmcnt(0)
	s_setprio 1
	s_waitcnt lgkmcnt(0)
	v_mfma_f32_16x16x32_bf16 v[108:111], v[202:205], v[150:153], v[108:111]
	v_mfma_f32_16x16x32_bf16 v[100:103], v[210:213], v[150:153], v[100:103]
	v_mfma_f32_16x16x32_bf16 v[92:95], v[202:205], v[164:167], v[92:95]
	v_mfma_f32_16x16x32_bf16 v[84:87], v[210:213], v[164:167], v[84:87]
	v_mfma_f32_16x16x32_bf16 v[76:79], v[202:205], v[172:175], v[76:79]
	v_mfma_f32_16x16x32_bf16 v[72:75], v[210:213], v[172:175], v[72:75]
	v_mfma_f32_16x16x32_bf16 v[68:71], v[202:205], v[194:197], v[68:71]
	v_mfma_f32_16x16x32_bf16 v[64:67], v[210:213], v[194:197], v[64:67]
	v_mfma_f32_16x16x32_bf16 v[108:111], v[206:209], v[154:157], v[108:111]
	v_mfma_f32_16x16x32_bf16 v[100:103], v[214:217], v[154:157], v[100:103]
	v_mfma_f32_16x16x32_bf16 v[92:95], v[206:209], v[168:171], v[92:95]
	v_mfma_f32_16x16x32_bf16 v[84:87], v[214:217], v[168:171], v[84:87]
	v_mfma_f32_16x16x32_bf16 v[76:79], v[206:209], v[190:193], v[76:79]
	v_mfma_f32_16x16x32_bf16 v[72:75], v[214:217], v[190:193], v[72:75]
	v_mfma_f32_16x16x32_bf16 v[68:71], v[206:209], v[198:201], v[68:71]
	v_mfma_f32_16x16x32_bf16 v[64:67], v[214:217], v[198:201], v[64:67]
	s_setprio 0
	s_mov_b32 m0, s46
	v_lshl_add_u64 v[158:159], v[220:221], 0, s[24:25]
	s_barrier
	ds_read_b128 v[150:153], v163 offset:49152
	ds_read_b128 v[154:157], v163 offset:50176
	ds_read_b128 v[164:167], v163 offset:51200
	ds_read_b128 v[168:171], v163 offset:52224
	ds_read_b128 v[172:175], v163 offset:53248
	ds_read_b128 v[190:193], v163 offset:54272
	ds_read_b128 v[194:197], v163 offset:55296
	ds_read_b128 v[198:201], v163 offset:56320
	global_load_lds_dwordx4 v[158:159], off
	v_lshl_add_u64 v[158:159], v[222:223], 0, s[24:25]
	s_mov_b32 m0, s47
	s_nop 0
	global_load_lds_dwordx4 v[158:159], off
	s_barrier
	s_waitcnt lgkmcnt(0)
	s_setprio 1
	s_waitcnt lgkmcnt(0)
	v_mfma_f32_16x16x32_bf16 v[60:63], v[128:131], v[150:153], v[60:63]
	v_mfma_f32_16x16x32_bf16 v[56:59], v[136:139], v[150:153], v[56:59]
	v_mfma_f32_16x16x32_bf16 v[52:55], v[128:131], v[164:167], v[52:55]
	v_mfma_f32_16x16x32_bf16 v[48:51], v[136:139], v[164:167], v[48:51]
	v_mfma_f32_16x16x32_bf16 v[40:43], v[128:131], v[172:175], v[40:43]
	v_mfma_f32_16x16x32_bf16 v[32:35], v[136:139], v[172:175], v[32:35]
	v_mfma_f32_16x16x32_bf16 v[24:27], v[128:131], v[194:197], v[24:27]
	v_mfma_f32_16x16x32_bf16 v[16:19], v[136:139], v[194:197], v[16:19]
	v_mfma_f32_16x16x32_bf16 v[60:63], v[132:135], v[154:157], v[60:63]
	v_mfma_f32_16x16x32_bf16 v[56:59], v[140:143], v[154:157], v[56:59]
	v_mfma_f32_16x16x32_bf16 v[52:55], v[132:135], v[168:171], v[52:55]
	v_mfma_f32_16x16x32_bf16 v[48:51], v[140:143], v[168:171], v[48:51]
	v_mfma_f32_16x16x32_bf16 v[40:43], v[132:135], v[190:193], v[40:43]
	v_mfma_f32_16x16x32_bf16 v[32:35], v[140:143], v[190:193], v[32:35]
	v_mfma_f32_16x16x32_bf16 v[24:27], v[132:135], v[198:201], v[24:27]
	v_mfma_f32_16x16x32_bf16 v[16:19], v[140:143], v[198:201], v[16:19]
	s_setprio 0
	s_barrier
	s_add_u32 s12, s16, 0xb0080
	s_addc_u32 s13, s17, 0
	s_add_i32 s16, s18, s34
	v_lshl_add_u64 v[128:129], s[12:13], 0, v[176:177]
	s_mov_b32 m0, s16
	s_nop 0
	global_load_lds_dwordx4 v[128:129], off
	v_lshl_add_u64 v[128:129], s[12:13], 0, v[144:145]
	s_add_i32 m0, s16, 0x2000
	s_nop 0
	global_load_lds_dwordx4 v[128:129], off
	s_waitcnt vmcnt(6)
	s_barrier
	s_setprio 1
	v_mfma_f32_16x16x32_bf16 v[44:47], v[202:205], v[150:153], v[44:47]
	v_mfma_f32_16x16x32_bf16 v[36:39], v[210:213], v[150:153], v[36:39]
	v_mfma_f32_16x16x32_bf16 v[28:31], v[202:205], v[164:167], v[28:31]
	v_mfma_f32_16x16x32_bf16 v[20:23], v[210:213], v[164:167], v[20:23]
	v_mfma_f32_16x16x32_bf16 v[12:15], v[202:205], v[172:175], v[12:15]
	v_mfma_f32_16x16x32_bf16 v[8:11], v[210:213], v[172:175], v[8:11]
	v_mfma_f32_16x16x32_bf16 v[4:7], v[202:205], v[194:197], v[4:7]
	v_mfma_f32_16x16x32_bf16 v[0:3], v[210:213], v[194:197], v[0:3]
	v_mfma_f32_16x16x32_bf16 v[44:47], v[206:209], v[154:157], v[44:47]
	v_mfma_f32_16x16x32_bf16 v[36:39], v[214:217], v[154:157], v[36:39]
	v_mfma_f32_16x16x32_bf16 v[28:31], v[206:209], v[168:171], v[28:31]
	v_mfma_f32_16x16x32_bf16 v[20:23], v[214:217], v[168:171], v[20:23]
	v_mfma_f32_16x16x32_bf16 v[12:15], v[206:209], v[190:193], v[12:15]
	v_mfma_f32_16x16x32_bf16 v[8:11], v[214:217], v[190:193], v[8:11]
	v_mfma_f32_16x16x32_bf16 v[4:7], v[206:209], v[198:201], v[4:7]
	v_mfma_f32_16x16x32_bf16 v[0:3], v[214:217], v[198:201], v[0:3]
	s_setprio 0
	s_add_u32 s58, s58, 0x100
	s_addc_u32 s59, s59, 0
	s_cmp_ge_i32 s60, s42
	s_mov_b64 s[12:13], s[14:15]
	s_mov_b32 s16, s60
	s_barrier
	s_cbranch_scc0 .LBB0_1787
	v_mov_b32_e32 v158, v161
	s_mov_b32 s12, s39
	v_mov_b32_e32 v128, v160
	s_mov_b32 s13, s28
	s_lshl_b32 s14, s41, 8
	s_lshl_b32 s13, s13, 6
	s_add_i32 s13, s13, s14
	v_add_u32_e32 v150, s13, v128
	s_lshl_b32 s13, s40, 8
	s_lshl_b32 s12, s12, 5
	s_add_i32 s12, s12, s13
	v_lshl_add_u32 v152, v158, 2, s12
	s_cmp_gt_i32 s23, 0
	v_ashrrev_i32_e32 v153, 31, v152
	s_mov_b64 s[12:13], -1
	s_cbranch_scc1 .LBB0_1950
	v_lshlrev_b32_e32 v151, 11, v150
	v_lshl_add_u32 v151, v152, 1, v151
	v_lshlrev_b32_e32 v190, 2, v150
	v_xor_b32_e32 v191, 16, v229
	v_xor_b32_e32 v153, 32, v229
	v_lshlrev_b32_e32 v191, 2, v191
	v_lshlrev_b32_e32 v153, 2, v153
	v_mov_b32_e32 v239, v151
	v_lshlrev_b32_e32 v150, 12, v150
	v_lshl_add_u32 v150, v152, 2, v150
	s_and_b64 vcc, exec, s[6:7]
	s_cbranch_vccnz .LresJ_yout
	v_mov_b32_e32 v238, v151
	global_load_dwordx2 v[192:193], v238, s[96:97]
	global_load_dwordx2 v[194:195], v238, s[96:97] offset:32
	global_load_dwordx2 v[196:197], v238, s[96:97] offset:256
	global_load_dwordx2 v[198:199], v238, s[96:97] offset:288
	v_add_u32_e32 v238, 0x8000, v238
	global_load_dwordx2 v[200:201], v238, s[96:97]
	global_load_dwordx2 v[202:203], v238, s[96:97] offset:32
	global_load_dwordx2 v[204:205], v238, s[96:97] offset:256
	global_load_dwordx2 v[206:207], v238, s[96:97] offset:288
	v_add_u32_e32 v238, 0x8000, v238
	global_load_dwordx2 v[208:209], v238, s[96:97]
	global_load_dwordx2 v[210:211], v238, s[96:97] offset:32
	global_load_dwordx2 v[212:213], v238, s[96:97] offset:256
	global_load_dwordx2 v[214:215], v238, s[96:97] offset:288
	v_add_u32_e32 v238, 0x8000, v238
	global_load_dwordx2 v[216:217], v238, s[96:97]
	global_load_dwordx2 v[218:219], v238, s[96:97] offset:32
	global_load_dwordx2 v[220:221], v238, s[96:97] offset:256
	global_load_dwordx2 v[222:223], v238, s[96:97] offset:288
	v_add_u32_e32 v238, 0x28000, v238
	global_load_dwordx2 v[128:129], v238, s[96:97]
	global_load_dwordx2 v[130:131], v238, s[96:97] offset:32
	global_load_dwordx2 v[132:133], v238, s[96:97] offset:256
	global_load_dwordx2 v[134:135], v238, s[96:97] offset:288
	v_add_u32_e32 v238, 0x8000, v238
	global_load_dwordx2 v[136:137], v238, s[96:97]
	global_load_dwordx2 v[138:139], v238, s[96:97] offset:32
	global_load_dwordx2 v[140:141], v238, s[96:97] offset:256
	global_load_dwordx2 v[142:143], v238, s[96:97] offset:288
	v_add_u32_e32 v238, 0x8000, v238
	global_load_dwordx2 v[164:165], v238, s[96:97]
	global_load_dwordx2 v[166:167], v238, s[96:97] offset:32
	global_load_dwordx2 v[168:169], v238, s[96:97] offset:256
	global_load_dwordx2 v[170:171], v238, s[96:97] offset:288
	v_add_u32_e32 v238, 0x8000, v238
	global_load_dwordx2 v[172:173], v238, s[96:97]
	global_load_dwordx2 v[174:175], v238, s[96:97] offset:32
	global_load_dwordx2 v[240:241], v238, s[96:97] offset:256
	global_load_dwordx2 v[242:243], v238, s[96:97] offset:288
	s_waitcnt vmcnt(31)
	v_lshlrev_b32_e32 v252, 16, v192
	v_and_b32_e32 v253, 0xffff0000, v192
	v_lshlrev_b32_e32 v254, 16, v193
	v_and_b32_e32 v255, 0xffff0000, v193
	v_pk_add_f32 v[252:253], v[124:125], v[252:253]
	v_pk_add_f32 v[254:255], v[126:127], v[254:255]
	v_mul_f32_e32 v154, v252, v252
	v_fmac_f32_e32 v154, v253, v253
	v_fmac_f32_e32 v154, v254, v254
	v_fmac_f32_e32 v154, v255, v255
	v_cvt_pk_bf16_f32 v158, v252, v253
	v_cvt_pk_bf16_f32 v159, v254, v255
	global_store_dwordx2 v239, v[158:159], s[96:97]
	s_waitcnt vmcnt(31)
	v_lshlrev_b32_e32 v252, 16, v194
	v_and_b32_e32 v253, 0xffff0000, v194
	v_lshlrev_b32_e32 v254, 16, v195
	v_and_b32_e32 v255, 0xffff0000, v195
	v_pk_add_f32 v[252:253], v[120:121], v[252:253]
	v_pk_add_f32 v[254:255], v[122:123], v[254:255]
	v_fmac_f32_e32 v154, v252, v252
	v_fmac_f32_e32 v154, v253, v253
	v_fmac_f32_e32 v154, v254, v254
	v_fmac_f32_e32 v154, v255, v255
	v_cvt_pk_bf16_f32 v158, v252, v253
	v_cvt_pk_bf16_f32 v159, v254, v255
	global_store_dwordx2 v239, v[158:159], s[96:97] offset:32
	s_waitcnt vmcnt(31)
	v_lshlrev_b32_e32 v252, 16, v196
	v_and_b32_e32 v253, 0xffff0000, v196
	v_lshlrev_b32_e32 v254, 16, v197
	v_and_b32_e32 v255, 0xffff0000, v197
	v_pk_add_f32 v[252:253], v[108:109], v[252:253]
	v_pk_add_f32 v[254:255], v[110:111], v[254:255]
	v_fmac_f32_e32 v154, v252, v252
	v_fmac_f32_e32 v154, v253, v253
	v_fmac_f32_e32 v154, v254, v254
	v_fmac_f32_e32 v154, v255, v255
	v_cvt_pk_bf16_f32 v158, v252, v253
	v_cvt_pk_bf16_f32 v159, v254, v255
	global_store_dwordx2 v239, v[158:159], s[96:97] offset:256
	s_waitcnt vmcnt(31)
	v_lshlrev_b32_e32 v252, 16, v198
	v_and_b32_e32 v253, 0xffff0000, v198
	v_lshlrev_b32_e32 v254, 16, v199
	v_and_b32_e32 v255, 0xffff0000, v199
	v_pk_add_f32 v[252:253], v[100:101], v[252:253]
	v_pk_add_f32 v[254:255], v[102:103], v[254:255]
	v_fmac_f32_e32 v154, v252, v252
	v_fmac_f32_e32 v154, v253, v253
	v_fmac_f32_e32 v154, v254, v254
	v_fmac_f32_e32 v154, v255, v255
	v_cvt_pk_bf16_f32 v158, v252, v253
	v_cvt_pk_bf16_f32 v159, v254, v255
	global_store_dwordx2 v239, v[158:159], s[96:97] offset:288
	v_add_u32_e32 v239, 0x8000, v239
	s_waitcnt vmcnt(31)
	v_lshlrev_b32_e32 v252, 16, v200
	v_and_b32_e32 v253, 0xffff0000, v200
	v_lshlrev_b32_e32 v254, 16, v201
	v_and_b32_e32 v255, 0xffff0000, v201
	v_pk_add_f32 v[252:253], v[116:117], v[252:253]
	v_pk_add_f32 v[254:255], v[118:119], v[254:255]
	v_mul_f32_e32 v155, v252, v252
	v_fmac_f32_e32 v155, v253, v253
	v_fmac_f32_e32 v155, v254, v254
	v_fmac_f32_e32 v155, v255, v255
	v_cvt_pk_bf16_f32 v158, v252, v253
	v_cvt_pk_bf16_f32 v159, v254, v255
	global_store_dwordx2 v239, v[158:159], s[96:97]
	s_waitcnt vmcnt(31)
	v_lshlrev_b32_e32 v252, 16, v202
	v_and_b32_e32 v253, 0xffff0000, v202
	v_lshlrev_b32_e32 v254, 16, v203
	v_and_b32_e32 v255, 0xffff0000, v203
	v_pk_add_f32 v[252:253], v[112:113], v[252:253]
	v_pk_add_f32 v[254:255], v[114:115], v[254:255]
	v_fmac_f32_e32 v155, v252, v252
	v_fmac_f32_e32 v155, v253, v253
	v_fmac_f32_e32 v155, v254, v254
	v_fmac_f32_e32 v155, v255, v255
	v_cvt_pk_bf16_f32 v158, v252, v253
	v_cvt_pk_bf16_f32 v159, v254, v255
	global_store_dwordx2 v239, v[158:159], s[96:97] offset:32
	s_waitcnt vmcnt(31)
	v_lshlrev_b32_e32 v252, 16, v204
	v_and_b32_e32 v253, 0xffff0000, v204
	v_lshlrev_b32_e32 v254, 16, v205
	v_and_b32_e32 v255, 0xffff0000, v205
	v_pk_add_f32 v[252:253], v[92:93], v[252:253]
	v_pk_add_f32 v[254:255], v[94:95], v[254:255]
	v_fmac_f32_e32 v155, v252, v252
	v_fmac_f32_e32 v155, v253, v253
	v_fmac_f32_e32 v155, v254, v254
	v_fmac_f32_e32 v155, v255, v255
	v_cvt_pk_bf16_f32 v158, v252, v253
	v_cvt_pk_bf16_f32 v159, v254, v255
	global_store_dwordx2 v239, v[158:159], s[96:97] offset:256
	s_waitcnt vmcnt(31)
	v_lshlrev_b32_e32 v252, 16, v206
	v_and_b32_e32 v253, 0xffff0000, v206
	v_lshlrev_b32_e32 v254, 16, v207
	v_and_b32_e32 v255, 0xffff0000, v207
	v_pk_add_f32 v[252:253], v[84:85], v[252:253]
	v_pk_add_f32 v[254:255], v[86:87], v[254:255]
	v_fmac_f32_e32 v155, v252, v252
	v_fmac_f32_e32 v155, v253, v253
	v_fmac_f32_e32 v155, v254, v254
	v_fmac_f32_e32 v155, v255, v255
	v_cvt_pk_bf16_f32 v158, v252, v253
	v_cvt_pk_bf16_f32 v159, v254, v255
	global_store_dwordx2 v239, v[158:159], s[96:97] offset:288
	v_add_u32_e32 v239, 0x8000, v239
	s_waitcnt vmcnt(31)
	v_lshlrev_b32_e32 v252, 16, v208
	v_and_b32_e32 v253, 0xffff0000, v208
	v_lshlrev_b32_e32 v254, 16, v209
	v_and_b32_e32 v255, 0xffff0000, v209
	v_pk_add_f32 v[252:253], v[104:105], v[252:253]
	v_pk_add_f32 v[254:255], v[106:107], v[254:255]
	v_mul_f32_e32 v156, v252, v252
	v_fmac_f32_e32 v156, v253, v253
	v_fmac_f32_e32 v156, v254, v254
	v_fmac_f32_e32 v156, v255, v255
	v_cvt_pk_bf16_f32 v158, v252, v253
	v_cvt_pk_bf16_f32 v159, v254, v255
	global_store_dwordx2 v239, v[158:159], s[96:97]
	s_waitcnt vmcnt(31)
	v_lshlrev_b32_e32 v252, 16, v210
	v_and_b32_e32 v253, 0xffff0000, v210
	v_lshlrev_b32_e32 v254, 16, v211
	v_and_b32_e32 v255, 0xffff0000, v211
	v_pk_add_f32 v[252:253], v[96:97], v[252:253]
	v_pk_add_f32 v[254:255], v[98:99], v[254:255]
	v_fmac_f32_e32 v156, v252, v252
	v_fmac_f32_e32 v156, v253, v253
	v_fmac_f32_e32 v156, v254, v254
	v_fmac_f32_e32 v156, v255, v255
	v_cvt_pk_bf16_f32 v158, v252, v253
	v_cvt_pk_bf16_f32 v159, v254, v255
	global_store_dwordx2 v239, v[158:159], s[96:97] offset:32
	s_waitcnt vmcnt(31)
	v_lshlrev_b32_e32 v252, 16, v212
	v_and_b32_e32 v253, 0xffff0000, v212
	v_lshlrev_b32_e32 v254, 16, v213
	v_and_b32_e32 v255, 0xffff0000, v213
	v_pk_add_f32 v[252:253], v[76:77], v[252:253]
	v_pk_add_f32 v[254:255], v[78:79], v[254:255]
	v_fmac_f32_e32 v156, v252, v252
	v_fmac_f32_e32 v156, v253, v253
	v_fmac_f32_e32 v156, v254, v254
	v_fmac_f32_e32 v156, v255, v255
	v_cvt_pk_bf16_f32 v158, v252, v253
	v_cvt_pk_bf16_f32 v159, v254, v255
	global_store_dwordx2 v239, v[158:159], s[96:97] offset:256
	s_waitcnt vmcnt(31)
	v_lshlrev_b32_e32 v252, 16, v214
	v_and_b32_e32 v253, 0xffff0000, v214
	v_lshlrev_b32_e32 v254, 16, v215
	v_and_b32_e32 v255, 0xffff0000, v215
	v_pk_add_f32 v[252:253], v[72:73], v[252:253]
	v_pk_add_f32 v[254:255], v[74:75], v[254:255]
	v_fmac_f32_e32 v156, v252, v252
	v_fmac_f32_e32 v156, v253, v253
	v_fmac_f32_e32 v156, v254, v254
	v_fmac_f32_e32 v156, v255, v255
	v_cvt_pk_bf16_f32 v158, v252, v253
	v_cvt_pk_bf16_f32 v159, v254, v255
	global_store_dwordx2 v239, v[158:159], s[96:97] offset:288
	v_add_u32_e32 v239, 0x8000, v239
	s_waitcnt vmcnt(31)
	v_lshlrev_b32_e32 v252, 16, v216
	v_and_b32_e32 v253, 0xffff0000, v216
	v_lshlrev_b32_e32 v254, 16, v217
	v_and_b32_e32 v255, 0xffff0000, v217
	v_pk_add_f32 v[252:253], v[88:89], v[252:253]
	v_pk_add_f32 v[254:255], v[90:91], v[254:255]
	v_mul_f32_e32 v157, v252, v252
	v_fmac_f32_e32 v157, v253, v253
	v_fmac_f32_e32 v157, v254, v254
	v_fmac_f32_e32 v157, v255, v255
	v_cvt_pk_bf16_f32 v158, v252, v253
	v_cvt_pk_bf16_f32 v159, v254, v255
	global_store_dwordx2 v239, v[158:159], s[96:97]
	s_waitcnt vmcnt(31)
	v_lshlrev_b32_e32 v252, 16, v218
	v_and_b32_e32 v253, 0xffff0000, v218
	v_lshlrev_b32_e32 v254, 16, v219
	v_and_b32_e32 v255, 0xffff0000, v219
	v_pk_add_f32 v[252:253], v[80:81], v[252:253]
	v_pk_add_f32 v[254:255], v[82:83], v[254:255]
	v_fmac_f32_e32 v157, v252, v252
	v_fmac_f32_e32 v157, v253, v253
	v_fmac_f32_e32 v157, v254, v254
	v_fmac_f32_e32 v157, v255, v255
	v_cvt_pk_bf16_f32 v158, v252, v253
	v_cvt_pk_bf16_f32 v159, v254, v255
	global_store_dwordx2 v239, v[158:159], s[96:97] offset:32
	s_waitcnt vmcnt(31)
	v_lshlrev_b32_e32 v252, 16, v220
	v_and_b32_e32 v253, 0xffff0000, v220
	v_lshlrev_b32_e32 v254, 16, v221
	v_and_b32_e32 v255, 0xffff0000, v221
	v_pk_add_f32 v[252:253], v[68:69], v[252:253]
	v_pk_add_f32 v[254:255], v[70:71], v[254:255]
	v_fmac_f32_e32 v157, v252, v252
	v_fmac_f32_e32 v157, v253, v253
	v_fmac_f32_e32 v157, v254, v254
	v_fmac_f32_e32 v157, v255, v255
	v_cvt_pk_bf16_f32 v158, v252, v253
	v_cvt_pk_bf16_f32 v159, v254, v255
	global_store_dwordx2 v239, v[158:159], s[96:97] offset:256
	s_waitcnt vmcnt(31)
	v_lshlrev_b32_e32 v252, 16, v222
	v_and_b32_e32 v253, 0xffff0000, v222
	v_lshlrev_b32_e32 v254, 16, v223
	v_and_b32_e32 v255, 0xffff0000, v223
	v_pk_add_f32 v[252:253], v[64:65], v[252:253]
	v_pk_add_f32 v[254:255], v[66:67], v[254:255]
	v_fmac_f32_e32 v157, v252, v252
	v_fmac_f32_e32 v157, v253, v253
	v_fmac_f32_e32 v157, v254, v254
	v_fmac_f32_e32 v157, v255, v255
	v_cvt_pk_bf16_f32 v158, v252, v253
	v_cvt_pk_bf16_f32 v159, v254, v255
	global_store_dwordx2 v239, v[158:159], s[96:97] offset:288
	v_add_u32_e32 v239, 0x28000, v239
	s_waitcnt vmcnt(31)
	v_lshlrev_b32_e32 v252, 16, v128
	v_and_b32_e32 v253, 0xffff0000, v128
	v_lshlrev_b32_e32 v254, 16, v129
	v_and_b32_e32 v255, 0xffff0000, v129
	v_pk_add_f32 v[252:253], v[60:61], v[252:253]
	v_pk_add_f32 v[254:255], v[62:63], v[254:255]
	v_mul_f32_e32 v244, v252, v252
	v_fmac_f32_e32 v244, v253, v253
	v_fmac_f32_e32 v244, v254, v254
	v_fmac_f32_e32 v244, v255, v255
	v_cvt_pk_bf16_f32 v158, v252, v253
	v_cvt_pk_bf16_f32 v159, v254, v255
	global_store_dwordx2 v239, v[158:159], s[96:97]
	s_waitcnt vmcnt(31)
	v_lshlrev_b32_e32 v252, 16, v130
	v_and_b32_e32 v253, 0xffff0000, v130
	v_lshlrev_b32_e32 v254, 16, v131
	v_and_b32_e32 v255, 0xffff0000, v131
	v_pk_add_f32 v[252:253], v[56:57], v[252:253]
	v_pk_add_f32 v[254:255], v[58:59], v[254:255]
	v_fmac_f32_e32 v244, v252, v252
	v_fmac_f32_e32 v244, v253, v253
	v_fmac_f32_e32 v244, v254, v254
	v_fmac_f32_e32 v244, v255, v255
	v_cvt_pk_bf16_f32 v158, v252, v253
	v_cvt_pk_bf16_f32 v159, v254, v255
	global_store_dwordx2 v239, v[158:159], s[96:97] offset:32
	s_waitcnt vmcnt(31)
	v_lshlrev_b32_e32 v252, 16, v132
	v_and_b32_e32 v253, 0xffff0000, v132
	v_lshlrev_b32_e32 v254, 16, v133
	v_and_b32_e32 v255, 0xffff0000, v133
	v_pk_add_f32 v[252:253], v[44:45], v[252:253]
	v_pk_add_f32 v[254:255], v[46:47], v[254:255]
	v_fmac_f32_e32 v244, v252, v252
	v_fmac_f32_e32 v244, v253, v253
	v_fmac_f32_e32 v244, v254, v254
	v_fmac_f32_e32 v244, v255, v255
	v_cvt_pk_bf16_f32 v158, v252, v253
	v_cvt_pk_bf16_f32 v159, v254, v255
	global_store_dwordx2 v239, v[158:159], s[96:97] offset:256
	s_waitcnt vmcnt(31)
	v_lshlrev_b32_e32 v252, 16, v134
	v_and_b32_e32 v253, 0xffff0000, v134
	v_lshlrev_b32_e32 v254, 16, v135
	v_and_b32_e32 v255, 0xffff0000, v135
	v_pk_add_f32 v[252:253], v[36:37], v[252:253]
	v_pk_add_f32 v[254:255], v[38:39], v[254:255]
	v_fmac_f32_e32 v244, v252, v252
	v_fmac_f32_e32 v244, v253, v253
	v_fmac_f32_e32 v244, v254, v254
	v_fmac_f32_e32 v244, v255, v255
	v_cvt_pk_bf16_f32 v158, v252, v253
	v_cvt_pk_bf16_f32 v159, v254, v255
	global_store_dwordx2 v239, v[158:159], s[96:97] offset:288
	v_add_u32_e32 v239, 0x8000, v239
	s_waitcnt vmcnt(31)
	v_lshlrev_b32_e32 v252, 16, v136
	v_and_b32_e32 v253, 0xffff0000, v136
	v_lshlrev_b32_e32 v254, 16, v137
	v_and_b32_e32 v255, 0xffff0000, v137
	v_pk_add_f32 v[252:253], v[52:53], v[252:253]
	v_pk_add_f32 v[254:255], v[54:55], v[254:255]
	v_mul_f32_e32 v245, v252, v252
	v_fmac_f32_e32 v245, v253, v253
	v_fmac_f32_e32 v245, v254, v254
	v_fmac_f32_e32 v245, v255, v255
	v_cvt_pk_bf16_f32 v158, v252, v253
	v_cvt_pk_bf16_f32 v159, v254, v255
	global_store_dwordx2 v239, v[158:159], s[96:97]
	s_waitcnt vmcnt(31)
	v_lshlrev_b32_e32 v252, 16, v138
	v_and_b32_e32 v253, 0xffff0000, v138
	v_lshlrev_b32_e32 v254, 16, v139
	v_and_b32_e32 v255, 0xffff0000, v139
	v_pk_add_f32 v[252:253], v[48:49], v[252:253]
	v_pk_add_f32 v[254:255], v[50:51], v[254:255]
	v_fmac_f32_e32 v245, v252, v252
	v_fmac_f32_e32 v245, v253, v253
	v_fmac_f32_e32 v245, v254, v254
	v_fmac_f32_e32 v245, v255, v255
	v_cvt_pk_bf16_f32 v158, v252, v253
	v_cvt_pk_bf16_f32 v159, v254, v255
	global_store_dwordx2 v239, v[158:159], s[96:97] offset:32
	s_waitcnt vmcnt(31)
	v_lshlrev_b32_e32 v252, 16, v140
	v_and_b32_e32 v253, 0xffff0000, v140
	v_lshlrev_b32_e32 v254, 16, v141
	v_and_b32_e32 v255, 0xffff0000, v141
	v_pk_add_f32 v[252:253], v[28:29], v[252:253]
	v_pk_add_f32 v[254:255], v[30:31], v[254:255]
	v_fmac_f32_e32 v245, v252, v252
	v_fmac_f32_e32 v245, v253, v253
	v_fmac_f32_e32 v245, v254, v254
	v_fmac_f32_e32 v245, v255, v255
	v_cvt_pk_bf16_f32 v158, v252, v253
	v_cvt_pk_bf16_f32 v159, v254, v255
	global_store_dwordx2 v239, v[158:159], s[96:97] offset:256
	s_waitcnt vmcnt(31)
	v_lshlrev_b32_e32 v252, 16, v142
	v_and_b32_e32 v253, 0xffff0000, v142
	v_lshlrev_b32_e32 v254, 16, v143
	v_and_b32_e32 v255, 0xffff0000, v143
	v_pk_add_f32 v[252:253], v[20:21], v[252:253]
	v_pk_add_f32 v[254:255], v[22:23], v[254:255]
	v_fmac_f32_e32 v245, v252, v252
	v_fmac_f32_e32 v245, v253, v253
	v_fmac_f32_e32 v245, v254, v254
	v_fmac_f32_e32 v245, v255, v255
	v_cvt_pk_bf16_f32 v158, v252, v253
	v_cvt_pk_bf16_f32 v159, v254, v255
	global_store_dwordx2 v239, v[158:159], s[96:97] offset:288
	v_add_u32_e32 v239, 0x8000, v239
	s_waitcnt vmcnt(31)
	v_lshlrev_b32_e32 v252, 16, v164
	v_and_b32_e32 v253, 0xffff0000, v164
	v_lshlrev_b32_e32 v254, 16, v165
	v_and_b32_e32 v255, 0xffff0000, v165
	v_pk_add_f32 v[252:253], v[40:41], v[252:253]
	v_pk_add_f32 v[254:255], v[42:43], v[254:255]
	v_mul_f32_e32 v246, v252, v252
	v_fmac_f32_e32 v246, v253, v253
	v_fmac_f32_e32 v246, v254, v254
	v_fmac_f32_e32 v246, v255, v255
	v_cvt_pk_bf16_f32 v158, v252, v253
	v_cvt_pk_bf16_f32 v159, v254, v255
	global_store_dwordx2 v239, v[158:159], s[96:97]
	s_waitcnt vmcnt(31)
	v_lshlrev_b32_e32 v252, 16, v166
	v_and_b32_e32 v253, 0xffff0000, v166
	v_lshlrev_b32_e32 v254, 16, v167
	v_and_b32_e32 v255, 0xffff0000, v167
	v_pk_add_f32 v[252:253], v[32:33], v[252:253]
	v_pk_add_f32 v[254:255], v[34:35], v[254:255]
	v_fmac_f32_e32 v246, v252, v252
	v_fmac_f32_e32 v246, v253, v253
	v_fmac_f32_e32 v246, v254, v254
	v_fmac_f32_e32 v246, v255, v255
	v_cvt_pk_bf16_f32 v158, v252, v253
	v_cvt_pk_bf16_f32 v159, v254, v255
	global_store_dwordx2 v239, v[158:159], s[96:97] offset:32
	s_waitcnt vmcnt(31)
	v_lshlrev_b32_e32 v252, 16, v168
	v_and_b32_e32 v253, 0xffff0000, v168
	v_lshlrev_b32_e32 v254, 16, v169
	v_and_b32_e32 v255, 0xffff0000, v169
	v_pk_add_f32 v[252:253], v[12:13], v[252:253]
	v_pk_add_f32 v[254:255], v[14:15], v[254:255]
	v_fmac_f32_e32 v246, v252, v252
	v_fmac_f32_e32 v246, v253, v253
	v_fmac_f32_e32 v246, v254, v254
	v_fmac_f32_e32 v246, v255, v255
	v_cvt_pk_bf16_f32 v158, v252, v253
	v_cvt_pk_bf16_f32 v159, v254, v255
	global_store_dwordx2 v239, v[158:159], s[96:97] offset:256
	s_waitcnt vmcnt(31)
	v_lshlrev_b32_e32 v252, 16, v170
	v_and_b32_e32 v253, 0xffff0000, v170
	v_lshlrev_b32_e32 v254, 16, v171
	v_and_b32_e32 v255, 0xffff0000, v171
	v_pk_add_f32 v[252:253], v[8:9], v[252:253]
	v_pk_add_f32 v[254:255], v[10:11], v[254:255]
	v_fmac_f32_e32 v246, v252, v252
	v_fmac_f32_e32 v246, v253, v253
	v_fmac_f32_e32 v246, v254, v254
	v_fmac_f32_e32 v246, v255, v255
	v_cvt_pk_bf16_f32 v158, v252, v253
	v_cvt_pk_bf16_f32 v159, v254, v255
	global_store_dwordx2 v239, v[158:159], s[96:97] offset:288
	v_add_u32_e32 v239, 0x8000, v239
	s_waitcnt vmcnt(31)
	v_lshlrev_b32_e32 v252, 16, v172
	v_and_b32_e32 v253, 0xffff0000, v172
	v_lshlrev_b32_e32 v254, 16, v173
	v_and_b32_e32 v255, 0xffff0000, v173
	v_pk_add_f32 v[252:253], v[24:25], v[252:253]
	v_pk_add_f32 v[254:255], v[26:27], v[254:255]
	v_mul_f32_e32 v247, v252, v252
	v_fmac_f32_e32 v247, v253, v253
	v_fmac_f32_e32 v247, v254, v254
	v_fmac_f32_e32 v247, v255, v255
	v_cvt_pk_bf16_f32 v158, v252, v253
	v_cvt_pk_bf16_f32 v159, v254, v255
	global_store_dwordx2 v239, v[158:159], s[96:97]
	s_waitcnt vmcnt(31)
	v_lshlrev_b32_e32 v252, 16, v174
	v_and_b32_e32 v253, 0xffff0000, v174
	v_lshlrev_b32_e32 v254, 16, v175
	v_and_b32_e32 v255, 0xffff0000, v175
	v_pk_add_f32 v[252:253], v[16:17], v[252:253]
	v_pk_add_f32 v[254:255], v[18:19], v[254:255]
	v_fmac_f32_e32 v247, v252, v252
	v_fmac_f32_e32 v247, v253, v253
	v_fmac_f32_e32 v247, v254, v254
	v_fmac_f32_e32 v247, v255, v255
	v_cvt_pk_bf16_f32 v158, v252, v253
	v_cvt_pk_bf16_f32 v159, v254, v255
	global_store_dwordx2 v239, v[158:159], s[96:97] offset:32
	s_waitcnt vmcnt(31)
	v_lshlrev_b32_e32 v252, 16, v240
	v_and_b32_e32 v253, 0xffff0000, v240
	v_lshlrev_b32_e32 v254, 16, v241
	v_and_b32_e32 v255, 0xffff0000, v241
	v_pk_add_f32 v[252:253], v[4:5], v[252:253]
	v_pk_add_f32 v[254:255], v[6:7], v[254:255]
	v_fmac_f32_e32 v247, v252, v252
	v_fmac_f32_e32 v247, v253, v253
	v_fmac_f32_e32 v247, v254, v254
	v_fmac_f32_e32 v247, v255, v255
	v_cvt_pk_bf16_f32 v158, v252, v253
	v_cvt_pk_bf16_f32 v159, v254, v255
	global_store_dwordx2 v239, v[158:159], s[96:97] offset:256
	s_waitcnt vmcnt(31)
	v_lshlrev_b32_e32 v252, 16, v242
	v_and_b32_e32 v253, 0xffff0000, v242
	v_lshlrev_b32_e32 v254, 16, v243
	v_and_b32_e32 v255, 0xffff0000, v243
	v_pk_add_f32 v[252:253], v[0:1], v[252:253]
	v_pk_add_f32 v[254:255], v[2:3], v[254:255]
	v_fmac_f32_e32 v247, v252, v252
	v_fmac_f32_e32 v247, v253, v253
	v_fmac_f32_e32 v247, v254, v254
	v_fmac_f32_e32 v247, v255, v255
	v_cvt_pk_bf16_f32 v158, v252, v253
	v_cvt_pk_bf16_f32 v159, v254, v255
	global_store_dwordx2 v239, v[158:159], s[96:97] offset:288
	s_branch .LresJ_red
.LresJ_yout:
	v_mov_b32_e32 v238, v151
	global_load_dwordx2 v[192:193], v238, s[96:97]
	global_load_dwordx2 v[194:195], v238, s[96:97] offset:32
	global_load_dwordx2 v[196:197], v238, s[96:97] offset:256
	global_load_dwordx2 v[198:199], v238, s[96:97] offset:288
	v_add_u32_e32 v238, 0x8000, v238
	global_load_dwordx2 v[200:201], v238, s[96:97]
	global_load_dwordx2 v[202:203], v238, s[96:97] offset:32
	global_load_dwordx2 v[204:205], v238, s[96:97] offset:256
	global_load_dwordx2 v[206:207], v238, s[96:97] offset:288
	v_add_u32_e32 v238, 0x8000, v238
	global_load_dwordx2 v[208:209], v238, s[96:97]
	global_load_dwordx2 v[210:211], v238, s[96:97] offset:32
	global_load_dwordx2 v[212:213], v238, s[96:97] offset:256
	global_load_dwordx2 v[214:215], v238, s[96:97] offset:288
	v_add_u32_e32 v238, 0x8000, v238
	global_load_dwordx2 v[216:217], v238, s[96:97]
	global_load_dwordx2 v[218:219], v238, s[96:97] offset:32
	global_load_dwordx2 v[220:221], v238, s[96:97] offset:256
	global_load_dwordx2 v[222:223], v238, s[96:97] offset:288
	v_add_u32_e32 v238, 0x28000, v238
	global_load_dwordx2 v[128:129], v238, s[96:97]
	global_load_dwordx2 v[130:131], v238, s[96:97] offset:32
	global_load_dwordx2 v[132:133], v238, s[96:97] offset:256
	global_load_dwordx2 v[134:135], v238, s[96:97] offset:288
	v_add_u32_e32 v238, 0x8000, v238
	global_load_dwordx2 v[136:137], v238, s[96:97]
	global_load_dwordx2 v[138:139], v238, s[96:97] offset:32
	global_load_dwordx2 v[140:141], v238, s[96:97] offset:256
	global_load_dwordx2 v[142:143], v238, s[96:97] offset:288
	v_add_u32_e32 v238, 0x8000, v238
	global_load_dwordx2 v[164:165], v238, s[96:97]
	global_load_dwordx2 v[166:167], v238, s[96:97] offset:32
	global_load_dwordx2 v[168:169], v238, s[96:97] offset:256
	global_load_dwordx2 v[170:171], v238, s[96:97] offset:288
	v_add_u32_e32 v238, 0x8000, v238
	global_load_dwordx2 v[172:173], v238, s[96:97]
	global_load_dwordx2 v[174:175], v238, s[96:97] offset:32
	global_load_dwordx2 v[240:241], v238, s[96:97] offset:256
	global_load_dwordx2 v[242:243], v238, s[96:97] offset:288
	s_waitcnt vmcnt(31)
	v_lshlrev_b32_e32 v252, 16, v192
	v_and_b32_e32 v253, 0xffff0000, v192
	v_lshlrev_b32_e32 v254, 16, v193
	v_and_b32_e32 v255, 0xffff0000, v193
	v_pk_add_f32 v[252:253], v[124:125], v[252:253]
	v_pk_add_f32 v[254:255], v[126:127], v[254:255]
	v_mul_f32_e32 v154, v252, v252
	v_fmac_f32_e32 v154, v253, v253
	v_fmac_f32_e32 v154, v254, v254
	v_fmac_f32_e32 v154, v255, v255
	global_store_dwordx4 v150, v[252:255], s[26:27]
	s_nop 1
	s_waitcnt vmcnt(31)
	v_lshlrev_b32_e32 v252, 16, v194
	v_and_b32_e32 v253, 0xffff0000, v194
	v_lshlrev_b32_e32 v254, 16, v195
	v_and_b32_e32 v255, 0xffff0000, v195
	v_pk_add_f32 v[252:253], v[120:121], v[252:253]
	v_pk_add_f32 v[254:255], v[122:123], v[254:255]
	v_fmac_f32_e32 v154, v252, v252
	v_fmac_f32_e32 v154, v253, v253
	v_fmac_f32_e32 v154, v254, v254
	v_fmac_f32_e32 v154, v255, v255
	global_store_dwordx4 v150, v[252:255], s[26:27] offset:64
	s_nop 1
	s_waitcnt vmcnt(31)
	v_lshlrev_b32_e32 v252, 16, v196
	v_and_b32_e32 v253, 0xffff0000, v196
	v_lshlrev_b32_e32 v254, 16, v197
	v_and_b32_e32 v255, 0xffff0000, v197
	v_pk_add_f32 v[252:253], v[108:109], v[252:253]
	v_pk_add_f32 v[254:255], v[110:111], v[254:255]
	v_fmac_f32_e32 v154, v252, v252
	v_fmac_f32_e32 v154, v253, v253
	v_fmac_f32_e32 v154, v254, v254
	v_fmac_f32_e32 v154, v255, v255
	global_store_dwordx4 v150, v[252:255], s[26:27] offset:512
	s_nop 1
	s_waitcnt vmcnt(31)
	v_lshlrev_b32_e32 v252, 16, v198
	v_and_b32_e32 v253, 0xffff0000, v198
	v_lshlrev_b32_e32 v254, 16, v199
	v_and_b32_e32 v255, 0xffff0000, v199
	v_pk_add_f32 v[252:253], v[100:101], v[252:253]
	v_pk_add_f32 v[254:255], v[102:103], v[254:255]
	v_fmac_f32_e32 v154, v252, v252
	v_fmac_f32_e32 v154, v253, v253
	v_fmac_f32_e32 v154, v254, v254
	v_fmac_f32_e32 v154, v255, v255
	global_store_dwordx4 v150, v[252:255], s[26:27] offset:576
	s_nop 1
	v_add_u32_e32 v150, 0x10000, v150
	s_waitcnt vmcnt(31)
	v_lshlrev_b32_e32 v252, 16, v200
	v_and_b32_e32 v253, 0xffff0000, v200
	v_lshlrev_b32_e32 v254, 16, v201
	v_and_b32_e32 v255, 0xffff0000, v201
	v_pk_add_f32 v[252:253], v[116:117], v[252:253]
	v_pk_add_f32 v[254:255], v[118:119], v[254:255]
	v_mul_f32_e32 v155, v252, v252
	v_fmac_f32_e32 v155, v253, v253
	v_fmac_f32_e32 v155, v254, v254
	v_fmac_f32_e32 v155, v255, v255
	global_store_dwordx4 v150, v[252:255], s[26:27]
	s_nop 1
	s_waitcnt vmcnt(31)
	v_lshlrev_b32_e32 v252, 16, v202
	v_and_b32_e32 v253, 0xffff0000, v202
	v_lshlrev_b32_e32 v254, 16, v203
	v_and_b32_e32 v255, 0xffff0000, v203
	v_pk_add_f32 v[252:253], v[112:113], v[252:253]
	v_pk_add_f32 v[254:255], v[114:115], v[254:255]
	v_fmac_f32_e32 v155, v252, v252
	v_fmac_f32_e32 v155, v253, v253
	v_fmac_f32_e32 v155, v254, v254
	v_fmac_f32_e32 v155, v255, v255
	global_store_dwordx4 v150, v[252:255], s[26:27] offset:64
	s_nop 1
	s_waitcnt vmcnt(31)
	v_lshlrev_b32_e32 v252, 16, v204
	v_and_b32_e32 v253, 0xffff0000, v204
	v_lshlrev_b32_e32 v254, 16, v205
	v_and_b32_e32 v255, 0xffff0000, v205
	v_pk_add_f32 v[252:253], v[92:93], v[252:253]
	v_pk_add_f32 v[254:255], v[94:95], v[254:255]
	v_fmac_f32_e32 v155, v252, v252
	v_fmac_f32_e32 v155, v253, v253
	v_fmac_f32_e32 v155, v254, v254
	v_fmac_f32_e32 v155, v255, v255
	global_store_dwordx4 v150, v[252:255], s[26:27] offset:512
	s_nop 1
	s_waitcnt vmcnt(31)
	v_lshlrev_b32_e32 v252, 16, v206
	v_and_b32_e32 v253, 0xffff0000, v206
	v_lshlrev_b32_e32 v254, 16, v207
	v_and_b32_e32 v255, 0xffff0000, v207
	v_pk_add_f32 v[252:253], v[84:85], v[252:253]
	v_pk_add_f32 v[254:255], v[86:87], v[254:255]
	v_fmac_f32_e32 v155, v252, v252
	v_fmac_f32_e32 v155, v253, v253
	v_fmac_f32_e32 v155, v254, v254
	v_fmac_f32_e32 v155, v255, v255
	global_store_dwordx4 v150, v[252:255], s[26:27] offset:576
	s_nop 1
	v_add_u32_e32 v150, 0x10000, v150
	s_waitcnt vmcnt(31)
	v_lshlrev_b32_e32 v252, 16, v208
	v_and_b32_e32 v253, 0xffff0000, v208
	v_lshlrev_b32_e32 v254, 16, v209
	v_and_b32_e32 v255, 0xffff0000, v209
	v_pk_add_f32 v[252:253], v[104:105], v[252:253]
	v_pk_add_f32 v[254:255], v[106:107], v[254:255]
	v_mul_f32_e32 v156, v252, v252
	v_fmac_f32_e32 v156, v253, v253
	v_fmac_f32_e32 v156, v254, v254
	v_fmac_f32_e32 v156, v255, v255
	global_store_dwordx4 v150, v[252:255], s[26:27]
	s_nop 1
	s_waitcnt vmcnt(31)
	v_lshlrev_b32_e32 v252, 16, v210
	v_and_b32_e32 v253, 0xffff0000, v210
	v_lshlrev_b32_e32 v254, 16, v211
	v_and_b32_e32 v255, 0xffff0000, v211
	v_pk_add_f32 v[252:253], v[96:97], v[252:253]
	v_pk_add_f32 v[254:255], v[98:99], v[254:255]
	v_fmac_f32_e32 v156, v252, v252
	v_fmac_f32_e32 v156, v253, v253
	v_fmac_f32_e32 v156, v254, v254
	v_fmac_f32_e32 v156, v255, v255
	global_store_dwordx4 v150, v[252:255], s[26:27] offset:64
	s_nop 1
	s_waitcnt vmcnt(31)
	v_lshlrev_b32_e32 v252, 16, v212
	v_and_b32_e32 v253, 0xffff0000, v212
	v_lshlrev_b32_e32 v254, 16, v213
	v_and_b32_e32 v255, 0xffff0000, v213
	v_pk_add_f32 v[252:253], v[76:77], v[252:253]
	v_pk_add_f32 v[254:255], v[78:79], v[254:255]
	v_fmac_f32_e32 v156, v252, v252
	v_fmac_f32_e32 v156, v253, v253
	v_fmac_f32_e32 v156, v254, v254
	v_fmac_f32_e32 v156, v255, v255
	global_store_dwordx4 v150, v[252:255], s[26:27] offset:512
	s_nop 1
	s_waitcnt vmcnt(31)
	v_lshlrev_b32_e32 v252, 16, v214
	v_and_b32_e32 v253, 0xffff0000, v214
	v_lshlrev_b32_e32 v254, 16, v215
	v_and_b32_e32 v255, 0xffff0000, v215
	v_pk_add_f32 v[252:253], v[72:73], v[252:253]
	v_pk_add_f32 v[254:255], v[74:75], v[254:255]
	v_fmac_f32_e32 v156, v252, v252
	v_fmac_f32_e32 v156, v253, v253
	v_fmac_f32_e32 v156, v254, v254
	v_fmac_f32_e32 v156, v255, v255
	global_store_dwordx4 v150, v[252:255], s[26:27] offset:576
	s_nop 1
	v_add_u32_e32 v150, 0x10000, v150
	s_waitcnt vmcnt(31)
	v_lshlrev_b32_e32 v252, 16, v216
	v_and_b32_e32 v253, 0xffff0000, v216
	v_lshlrev_b32_e32 v254, 16, v217
	v_and_b32_e32 v255, 0xffff0000, v217
	v_pk_add_f32 v[252:253], v[88:89], v[252:253]
	v_pk_add_f32 v[254:255], v[90:91], v[254:255]
	v_mul_f32_e32 v157, v252, v252
	v_fmac_f32_e32 v157, v253, v253
	v_fmac_f32_e32 v157, v254, v254
	v_fmac_f32_e32 v157, v255, v255
	global_store_dwordx4 v150, v[252:255], s[26:27]
	s_nop 1
	s_waitcnt vmcnt(31)
	v_lshlrev_b32_e32 v252, 16, v218
	v_and_b32_e32 v253, 0xffff0000, v218
	v_lshlrev_b32_e32 v254, 16, v219
	v_and_b32_e32 v255, 0xffff0000, v219
	v_pk_add_f32 v[252:253], v[80:81], v[252:253]
	v_pk_add_f32 v[254:255], v[82:83], v[254:255]
	v_fmac_f32_e32 v157, v252, v252
	v_fmac_f32_e32 v157, v253, v253
	v_fmac_f32_e32 v157, v254, v254
	v_fmac_f32_e32 v157, v255, v255
	global_store_dwordx4 v150, v[252:255], s[26:27] offset:64
	s_nop 1
	s_waitcnt vmcnt(31)
	v_lshlrev_b32_e32 v252, 16, v220
	v_and_b32_e32 v253, 0xffff0000, v220
	v_lshlrev_b32_e32 v254, 16, v221
	v_and_b32_e32 v255, 0xffff0000, v221
	v_pk_add_f32 v[252:253], v[68:69], v[252:253]
	v_pk_add_f32 v[254:255], v[70:71], v[254:255]
	v_fmac_f32_e32 v157, v252, v252
	v_fmac_f32_e32 v157, v253, v253
	v_fmac_f32_e32 v157, v254, v254
	v_fmac_f32_e32 v157, v255, v255
	global_store_dwordx4 v150, v[252:255], s[26:27] offset:512
	s_nop 1
	s_waitcnt vmcnt(31)
	v_lshlrev_b32_e32 v252, 16, v222
	v_and_b32_e32 v253, 0xffff0000, v222
	v_lshlrev_b32_e32 v254, 16, v223
	v_and_b32_e32 v255, 0xffff0000, v223
	v_pk_add_f32 v[252:253], v[64:65], v[252:253]
	v_pk_add_f32 v[254:255], v[66:67], v[254:255]
	v_fmac_f32_e32 v157, v252, v252
	v_fmac_f32_e32 v157, v253, v253
	v_fmac_f32_e32 v157, v254, v254
	v_fmac_f32_e32 v157, v255, v255
	global_store_dwordx4 v150, v[252:255], s[26:27] offset:576
	s_nop 1
	v_add_u32_e32 v150, 0x50000, v150
	s_waitcnt vmcnt(31)
	v_lshlrev_b32_e32 v252, 16, v128
	v_and_b32_e32 v253, 0xffff0000, v128
	v_lshlrev_b32_e32 v254, 16, v129
	v_and_b32_e32 v255, 0xffff0000, v129
	v_pk_add_f32 v[252:253], v[60:61], v[252:253]
	v_pk_add_f32 v[254:255], v[62:63], v[254:255]
	v_mul_f32_e32 v244, v252, v252
	v_fmac_f32_e32 v244, v253, v253
	v_fmac_f32_e32 v244, v254, v254
	v_fmac_f32_e32 v244, v255, v255
	global_store_dwordx4 v150, v[252:255], s[26:27]
	s_nop 1
	s_waitcnt vmcnt(31)
	v_lshlrev_b32_e32 v252, 16, v130
	v_and_b32_e32 v253, 0xffff0000, v130
	v_lshlrev_b32_e32 v254, 16, v131
	v_and_b32_e32 v255, 0xffff0000, v131
	v_pk_add_f32 v[252:253], v[56:57], v[252:253]
	v_pk_add_f32 v[254:255], v[58:59], v[254:255]
	v_fmac_f32_e32 v244, v252, v252
	v_fmac_f32_e32 v244, v253, v253
	v_fmac_f32_e32 v244, v254, v254
	v_fmac_f32_e32 v244, v255, v255
	global_store_dwordx4 v150, v[252:255], s[26:27] offset:64
	s_nop 1
	s_waitcnt vmcnt(31)
	v_lshlrev_b32_e32 v252, 16, v132
	v_and_b32_e32 v253, 0xffff0000, v132
	v_lshlrev_b32_e32 v254, 16, v133
	v_and_b32_e32 v255, 0xffff0000, v133
	v_pk_add_f32 v[252:253], v[44:45], v[252:253]
	v_pk_add_f32 v[254:255], v[46:47], v[254:255]
	v_fmac_f32_e32 v244, v252, v252
	v_fmac_f32_e32 v244, v253, v253
	v_fmac_f32_e32 v244, v254, v254
	v_fmac_f32_e32 v244, v255, v255
	global_store_dwordx4 v150, v[252:255], s[26:27] offset:512
	s_nop 1
	s_waitcnt vmcnt(31)
	v_lshlrev_b32_e32 v252, 16, v134
	v_and_b32_e32 v253, 0xffff0000, v134
	v_lshlrev_b32_e32 v254, 16, v135
	v_and_b32_e32 v255, 0xffff0000, v135
	v_pk_add_f32 v[252:253], v[36:37], v[252:253]
	v_pk_add_f32 v[254:255], v[38:39], v[254:255]
	v_fmac_f32_e32 v244, v252, v252
	v_fmac_f32_e32 v244, v253, v253
	v_fmac_f32_e32 v244, v254, v254
	v_fmac_f32_e32 v244, v255, v255
	global_store_dwordx4 v150, v[252:255], s[26:27] offset:576
	s_nop 1
	v_add_u32_e32 v150, 0x10000, v150
	s_waitcnt vmcnt(31)
	v_lshlrev_b32_e32 v252, 16, v136
	v_and_b32_e32 v253, 0xffff0000, v136
	v_lshlrev_b32_e32 v254, 16, v137
	v_and_b32_e32 v255, 0xffff0000, v137
	v_pk_add_f32 v[252:253], v[52:53], v[252:253]
	v_pk_add_f32 v[254:255], v[54:55], v[254:255]
	v_mul_f32_e32 v245, v252, v252
	v_fmac_f32_e32 v245, v253, v253
	v_fmac_f32_e32 v245, v254, v254
	v_fmac_f32_e32 v245, v255, v255
	global_store_dwordx4 v150, v[252:255], s[26:27]
	s_nop 1
	s_waitcnt vmcnt(31)
	v_lshlrev_b32_e32 v252, 16, v138
	v_and_b32_e32 v253, 0xffff0000, v138
	v_lshlrev_b32_e32 v254, 16, v139
	v_and_b32_e32 v255, 0xffff0000, v139
	v_pk_add_f32 v[252:253], v[48:49], v[252:253]
	v_pk_add_f32 v[254:255], v[50:51], v[254:255]
	v_fmac_f32_e32 v245, v252, v252
	v_fmac_f32_e32 v245, v253, v253
	v_fmac_f32_e32 v245, v254, v254
	v_fmac_f32_e32 v245, v255, v255
	global_store_dwordx4 v150, v[252:255], s[26:27] offset:64
	s_nop 1
	s_waitcnt vmcnt(31)
	v_lshlrev_b32_e32 v252, 16, v140
	v_and_b32_e32 v253, 0xffff0000, v140
	v_lshlrev_b32_e32 v254, 16, v141
	v_and_b32_e32 v255, 0xffff0000, v141
	v_pk_add_f32 v[252:253], v[28:29], v[252:253]
	v_pk_add_f32 v[254:255], v[30:31], v[254:255]
	v_fmac_f32_e32 v245, v252, v252
	v_fmac_f32_e32 v245, v253, v253
	v_fmac_f32_e32 v245, v254, v254
	v_fmac_f32_e32 v245, v255, v255
	global_store_dwordx4 v150, v[252:255], s[26:27] offset:512
	s_nop 1
	s_waitcnt vmcnt(31)
	v_lshlrev_b32_e32 v252, 16, v142
	v_and_b32_e32 v253, 0xffff0000, v142
	v_lshlrev_b32_e32 v254, 16, v143
	v_and_b32_e32 v255, 0xffff0000, v143
	v_pk_add_f32 v[252:253], v[20:21], v[252:253]
	v_pk_add_f32 v[254:255], v[22:23], v[254:255]
	v_fmac_f32_e32 v245, v252, v252
	v_fmac_f32_e32 v245, v253, v253
	v_fmac_f32_e32 v245, v254, v254
	v_fmac_f32_e32 v245, v255, v255
	global_store_dwordx4 v150, v[252:255], s[26:27] offset:576
	s_nop 1
	v_add_u32_e32 v150, 0x10000, v150
	s_waitcnt vmcnt(31)
	v_lshlrev_b32_e32 v252, 16, v164
	v_and_b32_e32 v253, 0xffff0000, v164
	v_lshlrev_b32_e32 v254, 16, v165
	v_and_b32_e32 v255, 0xffff0000, v165
	v_pk_add_f32 v[252:253], v[40:41], v[252:253]
	v_pk_add_f32 v[254:255], v[42:43], v[254:255]
	v_mul_f32_e32 v246, v252, v252
	v_fmac_f32_e32 v246, v253, v253
	v_fmac_f32_e32 v246, v254, v254
	v_fmac_f32_e32 v246, v255, v255
	global_store_dwordx4 v150, v[252:255], s[26:27]
	s_nop 1
	s_waitcnt vmcnt(31)
	v_lshlrev_b32_e32 v252, 16, v166
	v_and_b32_e32 v253, 0xffff0000, v166
	v_lshlrev_b32_e32 v254, 16, v167
	v_and_b32_e32 v255, 0xffff0000, v167
	v_pk_add_f32 v[252:253], v[32:33], v[252:253]
	v_pk_add_f32 v[254:255], v[34:35], v[254:255]
	v_fmac_f32_e32 v246, v252, v252
	v_fmac_f32_e32 v246, v253, v253
	v_fmac_f32_e32 v246, v254, v254
	v_fmac_f32_e32 v246, v255, v255
	global_store_dwordx4 v150, v[252:255], s[26:27] offset:64
	s_nop 1
	s_waitcnt vmcnt(31)
	v_lshlrev_b32_e32 v252, 16, v168
	v_and_b32_e32 v253, 0xffff0000, v168
	v_lshlrev_b32_e32 v254, 16, v169
	v_and_b32_e32 v255, 0xffff0000, v169
	v_pk_add_f32 v[252:253], v[12:13], v[252:253]
	v_pk_add_f32 v[254:255], v[14:15], v[254:255]
	v_fmac_f32_e32 v246, v252, v252
	v_fmac_f32_e32 v246, v253, v253
	v_fmac_f32_e32 v246, v254, v254
	v_fmac_f32_e32 v246, v255, v255
	global_store_dwordx4 v150, v[252:255], s[26:27] offset:512
	s_nop 1
	s_waitcnt vmcnt(31)
	v_lshlrev_b32_e32 v252, 16, v170
	v_and_b32_e32 v253, 0xffff0000, v170
	v_lshlrev_b32_e32 v254, 16, v171
	v_and_b32_e32 v255, 0xffff0000, v171
	v_pk_add_f32 v[252:253], v[8:9], v[252:253]
	v_pk_add_f32 v[254:255], v[10:11], v[254:255]
	v_fmac_f32_e32 v246, v252, v252
	v_fmac_f32_e32 v246, v253, v253
	v_fmac_f32_e32 v246, v254, v254
	v_fmac_f32_e32 v246, v255, v255
	global_store_dwordx4 v150, v[252:255], s[26:27] offset:576
	s_nop 1
	v_add_u32_e32 v150, 0x10000, v150
	s_waitcnt vmcnt(31)
	v_lshlrev_b32_e32 v252, 16, v172
	v_and_b32_e32 v253, 0xffff0000, v172
	v_lshlrev_b32_e32 v254, 16, v173
	v_and_b32_e32 v255, 0xffff0000, v173
	v_pk_add_f32 v[252:253], v[24:25], v[252:253]
	v_pk_add_f32 v[254:255], v[26:27], v[254:255]
	v_mul_f32_e32 v247, v252, v252
	v_fmac_f32_e32 v247, v253, v253
	v_fmac_f32_e32 v247, v254, v254
	v_fmac_f32_e32 v247, v255, v255
	global_store_dwordx4 v150, v[252:255], s[26:27]
	s_nop 1
	s_waitcnt vmcnt(31)
	v_lshlrev_b32_e32 v252, 16, v174
	v_and_b32_e32 v253, 0xffff0000, v174
	v_lshlrev_b32_e32 v254, 16, v175
	v_and_b32_e32 v255, 0xffff0000, v175
	v_pk_add_f32 v[252:253], v[16:17], v[252:253]
	v_pk_add_f32 v[254:255], v[18:19], v[254:255]
	v_fmac_f32_e32 v247, v252, v252
	v_fmac_f32_e32 v247, v253, v253
	v_fmac_f32_e32 v247, v254, v254
	v_fmac_f32_e32 v247, v255, v255
	global_store_dwordx4 v150, v[252:255], s[26:27] offset:64
	s_nop 1
	s_waitcnt vmcnt(31)
	v_lshlrev_b32_e32 v252, 16, v240
	v_and_b32_e32 v253, 0xffff0000, v240
	v_lshlrev_b32_e32 v254, 16, v241
	v_and_b32_e32 v255, 0xffff0000, v241
	v_pk_add_f32 v[252:253], v[4:5], v[252:253]
	v_pk_add_f32 v[254:255], v[6:7], v[254:255]
	v_fmac_f32_e32 v247, v252, v252
	v_fmac_f32_e32 v247, v253, v253
	v_fmac_f32_e32 v247, v254, v254
	v_fmac_f32_e32 v247, v255, v255
	global_store_dwordx4 v150, v[252:255], s[26:27] offset:512
	s_nop 1
	s_waitcnt vmcnt(31)
	v_lshlrev_b32_e32 v252, 16, v242
	v_and_b32_e32 v253, 0xffff0000, v242
	v_lshlrev_b32_e32 v254, 16, v243
	v_and_b32_e32 v255, 0xffff0000, v243
	v_pk_add_f32 v[252:253], v[0:1], v[252:253]
	v_pk_add_f32 v[254:255], v[2:3], v[254:255]
	v_fmac_f32_e32 v247, v252, v252
	v_fmac_f32_e32 v247, v253, v253
	v_fmac_f32_e32 v247, v254, v254
	v_fmac_f32_e32 v247, v255, v255
	global_store_dwordx4 v150, v[252:255], s[26:27] offset:576
	s_nop 1
	s_branch .LresJ_red
.LresJ_red:
	v_readlane_b32 s40, v250, 31
	v_readlane_b32 s41, v250, 32
	s_nop 0
	s_and_b64 vcc, exec, s[40:41]
	s_cbranch_vccz .LresJ_done
	ds_bpermute_b32 v192, v191, v154
	ds_bpermute_b32 v193, v191, v155
	ds_bpermute_b32 v194, v191, v156
	ds_bpermute_b32 v195, v191, v157
	ds_bpermute_b32 v196, v191, v244
	ds_bpermute_b32 v197, v191, v245
	ds_bpermute_b32 v198, v191, v246
	ds_bpermute_b32 v199, v191, v247
	s_waitcnt lgkmcnt(0)
	v_add_f32_e32 v154, v154, v192
	v_add_f32_e32 v155, v155, v193
	v_add_f32_e32 v156, v156, v194
	v_add_f32_e32 v157, v157, v195
	v_add_f32_e32 v244, v244, v196
	v_add_f32_e32 v245, v245, v197
	v_add_f32_e32 v246, v246, v198
	v_add_f32_e32 v247, v247, v199
	ds_bpermute_b32 v192, v153, v154
	ds_bpermute_b32 v193, v153, v155
	ds_bpermute_b32 v194, v153, v156
	ds_bpermute_b32 v195, v153, v157
	ds_bpermute_b32 v196, v153, v244
	ds_bpermute_b32 v197, v153, v245
	ds_bpermute_b32 v198, v153, v246
	ds_bpermute_b32 v199, v153, v247
	s_waitcnt lgkmcnt(0)
	v_add_f32_e32 v154, v154, v192
	v_add_f32_e32 v155, v155, v193
	v_add_f32_e32 v156, v156, v194
	v_add_f32_e32 v157, v157, v195
	v_add_f32_e32 v244, v244, v196
	v_add_f32_e32 v245, v245, v197
	v_add_f32_e32 v246, v246, v198
	v_add_f32_e32 v247, v247, v199
	v_cmp_eq_u32_e32 vcc, 0, v161
	s_and_saveexec_b64 s[40:41], vcc
	global_atomic_add_f32 v190, v154, s[4:5]
	global_atomic_add_f32 v190, v155, s[4:5] offset:64
	global_atomic_add_f32 v190, v156, s[4:5] offset:128
	global_atomic_add_f32 v190, v157, s[4:5] offset:192
	global_atomic_add_f32 v190, v244, s[4:5] offset:512
	global_atomic_add_f32 v190, v245, s[4:5] offset:576
	global_atomic_add_f32 v190, v246, s[4:5] offset:640
	global_atomic_add_f32 v190, v247, s[4:5] offset:704
	s_or_b64 exec, exec, s[40:41]
